# K-loop: load-segment scalar arithmetic and loop counters placed at the END of the preceding MFMA segment (before its closing barrier)
# speedup vs baseline: 1.0014x; 1.0014x over previous
.LBB0_175:
	s_add_i32 s88, s88, 2
	s_add_u32 s79, s79, 0x240000
	s_addc_u32 s97, s97, 0
	s_add_u32 s80, s80, 0x460000
	s_addc_u32 s81, s81, 0
	s_cmp_gt_u32 s88, 29
	s_barrier
	s_cbranch_scc1 .LBB0_184
.LBB0_176:
	s_mov_b32 m0, s55
	s_nop 0
	global_load_lds_dwordx4 v194, s[100:101]
	s_mov_b32 m0, s67
	s_nop 0
	global_load_lds_dwordx4 v196, s[100:101]
	v_add_u32_e32 v130, 0x10000, v243
	v_add_u32_e32 v142, 0x14000, v243
	ds_read_b128 v[146:149], v130
	ds_read_b128 v[150:153], v130 offset:1024
	ds_read_b128 v[154:157], v130 offset:2048
	ds_read_b128 v[158:161], v130 offset:3072
	ds_read_b128 v[130:133], v142
	ds_read_b128 v[134:137], v142 offset:1024
	ds_read_b128 v[138:141], v142 offset:2048
	ds_read_b128 v[142:145], v142 offset:3072
	v_lshl_add_u64 v[246:247], v[234:235], 0, s[80:81]
	s_add_i32 m0, s8, 0xc000
	s_waitcnt lgkmcnt(0)
	ds_read_b128 v[174:177], v244
	ds_read_b128 v[190:193], v244 offset:1024
	ds_read_b128 v[170:173], v244 offset:2048
	ds_read_b128 v[186:189], v244 offset:3072
	ds_read_b128 v[166:169], v244 offset:4096
	ds_read_b128 v[182:185], v244 offset:5120
	ds_read_b128 v[162:165], v244 offset:6144
	ds_read_b128 v[178:181], v244 offset:7168
	global_load_lds_dwordx4 v[246:247], off
	v_lshl_add_u64 v[246:247], v[236:237], 0, s[80:81]
	s_add_i32 m0, s8, 0xe000
	s_nop 0
	global_load_lds_dwordx4 v[246:247], off
	s_waitcnt vmcnt(8) lgkmcnt(0)
	s_barrier
	v_mfma_f32_16x16x32_bf16 v[118:121], v[146:149], v[174:177], v[118:121]
	v_mfma_f32_16x16x32_bf16 v[126:129], v[154:157], v[174:177], v[126:129]
	v_mfma_f32_16x16x32_bf16 v[102:105], v[146:149], v[170:173], v[102:105]
	v_mfma_f32_16x16x32_bf16 v[110:113], v[154:157], v[170:173], v[110:113]
	v_mfma_f32_16x16x32_bf16 v[86:89], v[146:149], v[166:169], v[86:89]
	v_mfma_f32_16x16x32_bf16 v[94:97], v[154:157], v[166:169], v[94:97]
	v_mfma_f32_16x16x32_bf16 v[70:73], v[146:149], v[162:165], v[70:73]
	v_mfma_f32_16x16x32_bf16 v[78:81], v[154:157], v[162:165], v[78:81]
	v_mfma_f32_16x16x32_bf16 v[118:121], v[150:153], v[190:193], v[118:121]
	v_mfma_f32_16x16x32_bf16 v[126:129], v[158:161], v[190:193], v[126:129]
	v_mfma_f32_16x16x32_bf16 v[102:105], v[150:153], v[186:189], v[102:105]
	v_mfma_f32_16x16x32_bf16 v[110:113], v[158:161], v[186:189], v[110:113]
	v_mfma_f32_16x16x32_bf16 v[86:89], v[150:153], v[182:185], v[86:89]
	v_mfma_f32_16x16x32_bf16 v[94:97], v[158:161], v[182:185], v[94:97]
	v_mfma_f32_16x16x32_bf16 v[70:73], v[150:153], v[178:181], v[70:73]
	v_mfma_f32_16x16x32_bf16 v[78:81], v[158:161], v[178:181], v[78:81]
	v_mfma_f32_16x16x32_bf16 v[122:125], v[130:133], v[174:177], v[122:125]
	v_mfma_f32_16x16x32_bf16 v[114:117], v[138:141], v[174:177], v[114:117]
	v_mfma_f32_16x16x32_bf16 v[106:109], v[130:133], v[170:173], v[106:109]
	v_mfma_f32_16x16x32_bf16 v[98:101], v[138:141], v[170:173], v[98:101]
	v_mfma_f32_16x16x32_bf16 v[90:93], v[130:133], v[166:169], v[90:93]
	v_mfma_f32_16x16x32_bf16 v[82:85], v[138:141], v[166:169], v[82:85]
	v_mfma_f32_16x16x32_bf16 v[74:77], v[130:133], v[162:165], v[74:77]
	v_mfma_f32_16x16x32_bf16 v[66:69], v[138:141], v[162:165], v[66:69]
	v_mfma_f32_16x16x32_bf16 v[122:125], v[134:137], v[190:193], v[122:125]
	v_mfma_f32_16x16x32_bf16 v[114:117], v[142:145], v[190:193], v[114:117]
	v_mfma_f32_16x16x32_bf16 v[106:109], v[134:137], v[186:189], v[106:109]
	v_mfma_f32_16x16x32_bf16 v[98:101], v[142:145], v[186:189], v[98:101]
	v_mfma_f32_16x16x32_bf16 v[90:93], v[134:137], v[182:185], v[90:93]
	v_mfma_f32_16x16x32_bf16 v[82:85], v[142:145], v[182:185], v[82:85]
	v_mfma_f32_16x16x32_bf16 v[74:77], v[134:137], v[178:181], v[74:77]
	v_mfma_f32_16x16x32_bf16 v[66:69], v[142:145], v[178:181], v[66:69]
	s_add_u32 s82, s0, s80
	s_addc_u32 s83, s1, s81
	s_add_u32 s84, s82, 0x460000
	s_addc_u32 s85, s83, 0
	s_cmp_eq_u32 s80, 0x41a0000
	s_cselect_b64 s[86:87], -1, 0
	s_and_b64 s[82:83], s[86:87], exec
	s_cselect_b32 s83, s71, s97
	s_cselect_b32 s82, s73, s79
	s_cselect_b32 s85, s22, s85
	s_cselect_b32 s84, s69, s84
	s_barrier
	s_andn2_b64 s[48:49], exec, s[50:51]
	s_andn2_b64 vcc, exec, s[50:51]
	s_cbranch_vccnz .LBB0_178
	ds_read_b128 v[174:177], v244 offset:16384
	ds_read_b128 v[190:193], v244 offset:17408
	ds_read_b128 v[170:173], v244 offset:18432
	ds_read_b128 v[186:189], v244 offset:19456
	ds_read_b128 v[166:169], v244 offset:20480
	ds_read_b128 v[182:185], v244 offset:21504
	ds_read_b128 v[162:165], v244 offset:22528
	ds_read_b128 v[178:181], v244 offset:23552
.LBB0_178:
	s_mov_b32 m0, s9
	s_add_u32 vcc_lo, s82, 0x4000
	global_load_lds_dwordx4 v194, s[82:83]
	s_mov_b32 m0, s10
	s_addc_u32 vcc_hi, s83, 0
	global_load_lds_dwordx4 v196, s[82:83]
	s_mov_b32 m0, s11
	s_nop 0
	global_load_lds_dwordx4 v194, vcc
	v_lshl_add_u64 v[246:247], vcc, 0, v[196:197]
	s_mov_b32 m0, s12
	s_and_b64 vcc, exec, s[48:49]
	global_load_lds_dwordx4 v[246:247], off
	s_mov_b64 s[98:99], s[84:85]
	s_waitcnt vmcnt(6) lgkmcnt(0)
	s_barrier
	s_cbranch_vccnz .LBB0_180
	s_waitcnt lgkmcnt(0)
	v_mfma_f32_16x16x32_bf16 v[54:57], v[146:149], v[174:177], v[54:57]
	v_mfma_f32_16x16x32_bf16 v[62:65], v[154:157], v[174:177], v[62:65]
	v_mfma_f32_16x16x32_bf16 v[38:41], v[146:149], v[170:173], v[38:41]
	v_mfma_f32_16x16x32_bf16 v[46:49], v[154:157], v[170:173], v[46:49]
	v_mfma_f32_16x16x32_bf16 v[22:25], v[146:149], v[166:169], v[22:25]
	v_mfma_f32_16x16x32_bf16 v[30:33], v[154:157], v[166:169], v[30:33]
	v_mfma_f32_16x16x32_bf16 v[10:13], v[146:149], v[162:165], v[10:13]
	v_mfma_f32_16x16x32_bf16 v[14:17], v[154:157], v[162:165], v[14:17]
	v_mfma_f32_16x16x32_bf16 v[54:57], v[150:153], v[190:193], v[54:57]
	v_mfma_f32_16x16x32_bf16 v[62:65], v[158:161], v[190:193], v[62:65]
	v_mfma_f32_16x16x32_bf16 v[38:41], v[150:153], v[186:189], v[38:41]
	v_mfma_f32_16x16x32_bf16 v[46:49], v[158:161], v[186:189], v[46:49]
	v_mfma_f32_16x16x32_bf16 v[22:25], v[150:153], v[182:185], v[22:25]
	v_mfma_f32_16x16x32_bf16 v[30:33], v[158:161], v[182:185], v[30:33]
	v_mfma_f32_16x16x32_bf16 v[10:13], v[150:153], v[178:181], v[10:13]
	v_mfma_f32_16x16x32_bf16 v[14:17], v[158:161], v[178:181], v[14:17]
	v_mfma_f32_16x16x32_bf16 v[58:61], v[130:133], v[174:177], v[58:61]
	v_mfma_f32_16x16x32_bf16 v[50:53], v[138:141], v[174:177], v[50:53]
	v_mfma_f32_16x16x32_bf16 v[42:45], v[130:133], v[170:173], v[42:45]
	v_mfma_f32_16x16x32_bf16 v[34:37], v[138:141], v[170:173], v[34:37]
	v_mfma_f32_16x16x32_bf16 v[26:29], v[130:133], v[166:169], v[26:29]
	v_mfma_f32_16x16x32_bf16 v[18:21], v[138:141], v[166:169], v[18:21]
	v_mfma_f32_16x16x32_bf16 v[6:9], v[130:133], v[162:165], v[6:9]
	v_mfma_f32_16x16x32_bf16 v[2:5], v[138:141], v[162:165], v[2:5]
	v_mfma_f32_16x16x32_bf16 v[58:61], v[134:137], v[190:193], v[58:61]
	v_mfma_f32_16x16x32_bf16 v[50:53], v[142:145], v[190:193], v[50:53]
	v_mfma_f32_16x16x32_bf16 v[42:45], v[134:137], v[186:189], v[42:45]
	v_mfma_f32_16x16x32_bf16 v[34:37], v[142:145], v[186:189], v[34:37]
	v_mfma_f32_16x16x32_bf16 v[26:29], v[134:137], v[182:185], v[26:29]
	v_mfma_f32_16x16x32_bf16 v[18:21], v[142:145], v[182:185], v[18:21]
	v_mfma_f32_16x16x32_bf16 v[6:9], v[134:137], v[178:181], v[6:9]
	v_mfma_f32_16x16x32_bf16 v[2:5], v[142:145], v[178:181], v[2:5]
.LBB0_180:
	s_and_b64 vcc, s[46:47], s[86:87]
	v_cndmask_b32_e64 v131, v233, 0, vcc
	v_cndmask_b32_e32 v130, v232, v198, vcc
	v_lshl_add_u64 v[246:247], s[84:85], 0, v[130:131]
	s_barrier
	s_mov_b32 m0, s8
	s_nop 0
	global_load_lds_dwordx4 v194, s[98:99]
	s_mov_b32 m0, s13
	s_nop 0
	global_load_lds_dwordx4 v196, s[98:99]
	v_add_u32_e32 v130, 0x18000, v243
	v_add_u32_e32 v142, 0x1c000, v243
	ds_read_b128 v[146:149], v130
	ds_read_b128 v[150:153], v130 offset:1024
	ds_read_b128 v[154:157], v130 offset:2048
	ds_read_b128 v[158:161], v130 offset:3072
	ds_read_b128 v[130:133], v142
	ds_read_b128 v[134:137], v142 offset:1024
	ds_read_b128 v[138:141], v142 offset:2048
	ds_read_b128 v[142:145], v142 offset:3072
	s_mov_b32 m0, s14
	v_lshl_add_u64 v[248:249], v[246:247], 0, v[194:195]
	s_waitcnt lgkmcnt(0)
	ds_read_b128 v[174:177], v244 offset:32768
	ds_read_b128 v[190:193], v244 offset:33792
	ds_read_b128 v[170:173], v244 offset:34816
	ds_read_b128 v[186:189], v244 offset:35840
	ds_read_b128 v[166:169], v244 offset:36864
	ds_read_b128 v[182:185], v244 offset:37888
	ds_read_b128 v[162:165], v244 offset:38912
	ds_read_b128 v[178:181], v244 offset:39936
	global_load_lds_dwordx4 v[248:249], off
	v_lshl_add_u64 v[246:247], v[246:247], 0, v[196:197]
	s_mov_b32 m0, s15
	s_nop 0
	global_load_lds_dwordx4 v[246:247], off
	s_waitcnt vmcnt(8) lgkmcnt(0)
	s_barrier
	v_mfma_f32_16x16x32_bf16 v[118:121], v[146:149], v[174:177], v[118:121]
	v_mfma_f32_16x16x32_bf16 v[126:129], v[154:157], v[174:177], v[126:129]
	v_mfma_f32_16x16x32_bf16 v[102:105], v[146:149], v[170:173], v[102:105]
	v_mfma_f32_16x16x32_bf16 v[110:113], v[154:157], v[170:173], v[110:113]
	v_mfma_f32_16x16x32_bf16 v[86:89], v[146:149], v[166:169], v[86:89]
	v_mfma_f32_16x16x32_bf16 v[94:97], v[154:157], v[166:169], v[94:97]
	v_mfma_f32_16x16x32_bf16 v[70:73], v[146:149], v[162:165], v[70:73]
	v_mfma_f32_16x16x32_bf16 v[78:81], v[154:157], v[162:165], v[78:81]
	v_mfma_f32_16x16x32_bf16 v[118:121], v[150:153], v[190:193], v[118:121]
	v_mfma_f32_16x16x32_bf16 v[126:129], v[158:161], v[190:193], v[126:129]
	v_mfma_f32_16x16x32_bf16 v[102:105], v[150:153], v[186:189], v[102:105]
	v_mfma_f32_16x16x32_bf16 v[110:113], v[158:161], v[186:189], v[110:113]
	v_mfma_f32_16x16x32_bf16 v[86:89], v[150:153], v[182:185], v[86:89]
	v_mfma_f32_16x16x32_bf16 v[94:97], v[158:161], v[182:185], v[94:97]
	v_mfma_f32_16x16x32_bf16 v[70:73], v[150:153], v[178:181], v[70:73]
	v_mfma_f32_16x16x32_bf16 v[78:81], v[158:161], v[178:181], v[78:81]
	v_mfma_f32_16x16x32_bf16 v[122:125], v[130:133], v[174:177], v[122:125]
	v_mfma_f32_16x16x32_bf16 v[114:117], v[138:141], v[174:177], v[114:117]
	v_mfma_f32_16x16x32_bf16 v[106:109], v[130:133], v[170:173], v[106:109]
	v_mfma_f32_16x16x32_bf16 v[98:101], v[138:141], v[170:173], v[98:101]
	v_mfma_f32_16x16x32_bf16 v[90:93], v[130:133], v[166:169], v[90:93]
	v_mfma_f32_16x16x32_bf16 v[82:85], v[138:141], v[166:169], v[82:85]
	v_mfma_f32_16x16x32_bf16 v[74:77], v[130:133], v[162:165], v[74:77]
	v_mfma_f32_16x16x32_bf16 v[66:69], v[138:141], v[162:165], v[66:69]
	v_mfma_f32_16x16x32_bf16 v[122:125], v[134:137], v[190:193], v[122:125]
	v_mfma_f32_16x16x32_bf16 v[114:117], v[142:145], v[190:193], v[114:117]
	v_mfma_f32_16x16x32_bf16 v[106:109], v[134:137], v[186:189], v[106:109]
	v_mfma_f32_16x16x32_bf16 v[98:101], v[142:145], v[186:189], v[98:101]
	v_mfma_f32_16x16x32_bf16 v[90:93], v[134:137], v[182:185], v[90:93]
	v_mfma_f32_16x16x32_bf16 v[82:85], v[142:145], v[182:185], v[82:85]
	v_mfma_f32_16x16x32_bf16 v[74:77], v[134:137], v[178:181], v[74:77]
	v_mfma_f32_16x16x32_bf16 v[66:69], v[142:145], v[178:181], v[66:69]
	s_add_u32 s86, s82, 0x120000
	s_addc_u32 s87, s83, 0
	s_add_u32 s84, s84, 0x230000
	s_addc_u32 s85, s85, 0
	s_barrier
	s_and_b64 vcc, exec, s[48:49]
	s_cbranch_vccnz .LBB0_182
	ds_read_b128 v[174:177], v244 offset:49152
	ds_read_b128 v[190:193], v244 offset:50176
	ds_read_b128 v[170:173], v244 offset:51200
	ds_read_b128 v[186:189], v244 offset:52224
	ds_read_b128 v[166:169], v244 offset:53248
	ds_read_b128 v[182:185], v244 offset:54272
	ds_read_b128 v[162:165], v244 offset:55296
	ds_read_b128 v[178:181], v244 offset:56320
.LBB0_182:
	s_mov_b32 m0, s17
	s_add_u32 s82, s82, 0x124000
	global_load_lds_dwordx4 v194, s[86:87]
	s_mov_b32 m0, s54
	s_addc_u32 s83, s83, 0
	global_load_lds_dwordx4 v196, s[86:87]
	s_mov_b32 m0, s89
	s_and_b64 vcc, exec, s[48:49]
	global_load_lds_dwordx4 v194, s[82:83]
	s_mov_b32 m0, s90
	s_nop 0
	global_load_lds_dwordx4 v196, s[82:83]
	s_mov_b64 s[100:101], s[84:85]
	s_waitcnt vmcnt(6) lgkmcnt(0)
	s_barrier
	s_cbranch_vccnz .LBB0_175
	s_waitcnt lgkmcnt(0)
	v_mfma_f32_16x16x32_bf16 v[54:57], v[146:149], v[174:177], v[54:57]
	v_mfma_f32_16x16x32_bf16 v[62:65], v[154:157], v[174:177], v[62:65]
	v_mfma_f32_16x16x32_bf16 v[38:41], v[146:149], v[170:173], v[38:41]
	v_mfma_f32_16x16x32_bf16 v[46:49], v[154:157], v[170:173], v[46:49]
	v_mfma_f32_16x16x32_bf16 v[22:25], v[146:149], v[166:169], v[22:25]
	v_mfma_f32_16x16x32_bf16 v[30:33], v[154:157], v[166:169], v[30:33]
	v_mfma_f32_16x16x32_bf16 v[10:13], v[146:149], v[162:165], v[10:13]
	v_mfma_f32_16x16x32_bf16 v[14:17], v[154:157], v[162:165], v[14:17]
	v_mfma_f32_16x16x32_bf16 v[54:57], v[150:153], v[190:193], v[54:57]
	v_mfma_f32_16x16x32_bf16 v[62:65], v[158:161], v[190:193], v[62:65]
	v_mfma_f32_16x16x32_bf16 v[38:41], v[150:153], v[186:189], v[38:41]
	v_mfma_f32_16x16x32_bf16 v[46:49], v[158:161], v[186:189], v[46:49]
	v_mfma_f32_16x16x32_bf16 v[22:25], v[150:153], v[182:185], v[22:25]
	v_mfma_f32_16x16x32_bf16 v[30:33], v[158:161], v[182:185], v[30:33]
	v_mfma_f32_16x16x32_bf16 v[10:13], v[150:153], v[178:181], v[10:13]
	v_mfma_f32_16x16x32_bf16 v[14:17], v[158:161], v[178:181], v[14:17]
	v_mfma_f32_16x16x32_bf16 v[58:61], v[130:133], v[174:177], v[58:61]
	v_mfma_f32_16x16x32_bf16 v[50:53], v[138:141], v[174:177], v[50:53]
	v_mfma_f32_16x16x32_bf16 v[42:45], v[130:133], v[170:173], v[42:45]
	v_mfma_f32_16x16x32_bf16 v[34:37], v[138:141], v[170:173], v[34:37]
	v_mfma_f32_16x16x32_bf16 v[26:29], v[130:133], v[166:169], v[26:29]
	v_mfma_f32_16x16x32_bf16 v[18:21], v[138:141], v[166:169], v[18:21]
	v_mfma_f32_16x16x32_bf16 v[6:9], v[130:133], v[162:165], v[6:9]
	v_mfma_f32_16x16x32_bf16 v[2:5], v[138:141], v[162:165], v[2:5]
	v_mfma_f32_16x16x32_bf16 v[58:61], v[134:137], v[190:193], v[58:61]
	v_mfma_f32_16x16x32_bf16 v[50:53], v[142:145], v[190:193], v[50:53]
	v_mfma_f32_16x16x32_bf16 v[42:45], v[134:137], v[186:189], v[42:45]
	v_mfma_f32_16x16x32_bf16 v[34:37], v[142:145], v[186:189], v[34:37]
	v_mfma_f32_16x16x32_bf16 v[26:29], v[134:137], v[182:185], v[26:29]
	v_mfma_f32_16x16x32_bf16 v[18:21], v[142:145], v[182:185], v[18:21]
	v_mfma_f32_16x16x32_bf16 v[6:9], v[134:137], v[178:181], v[6:9]
	v_mfma_f32_16x16x32_bf16 v[2:5], v[142:145], v[178:181], v[2:5]
	s_branch .LBB0_175

.LBB0_558:
	s_add_i32 s73, s73, 2
	s_add_u32 s53, s53, 0x80000
	s_addc_u32 s72, s72, 0
	s_add_u32 s58, s58, 0x440000
	s_addc_u32 s59, s59, 0
	s_cmp_gt_u32 s73, 29
	s_barrier
	s_cbranch_scc1 .LBB0_567
.LBB0_559:
	s_mov_b32 m0, s55
	s_nop 0
	global_load_lds_dwordx4 v194, s[100:101]
	s_mov_b32 m0, s67
	s_nop 0
	global_load_lds_dwordx4 v196, s[100:101]
	ds_read_b128 v[146:149], v227
	ds_read_b128 v[150:153], v227 offset:1024
	ds_read_b128 v[154:157], v227 offset:2048
	ds_read_b128 v[158:161], v227 offset:3072
	ds_read_b128 v[130:133], v228
	ds_read_b128 v[134:137], v228 offset:1024
	ds_read_b128 v[138:141], v228 offset:2048
	ds_read_b128 v[142:145], v228 offset:3072
	v_lshl_add_u64 v[234:235], v[216:217], 0, s[58:59]
	s_add_i32 m0, s8, 0xc000
	s_waitcnt lgkmcnt(0)
	ds_read_b128 v[174:177], v229
	ds_read_b128 v[190:193], v229 offset:1024
	ds_read_b128 v[170:173], v229 offset:2048
	ds_read_b128 v[186:189], v229 offset:3072
	ds_read_b128 v[166:169], v229 offset:4096
	ds_read_b128 v[182:185], v229 offset:5120
	ds_read_b128 v[162:165], v229 offset:6144
	ds_read_b128 v[178:181], v229 offset:7168
	global_load_lds_dwordx4 v[234:235], off
	v_lshl_add_u64 v[234:235], v[218:219], 0, s[58:59]
	s_add_i32 m0, s8, 0xe000
	s_nop 0
	global_load_lds_dwordx4 v[234:235], off
	s_waitcnt vmcnt(8) lgkmcnt(0)
	s_barrier
	v_mfma_f32_16x16x32_bf16 v[126:129], v[146:149], v[174:177], v[126:129]
	v_mfma_f32_16x16x32_bf16 v[122:125], v[154:157], v[174:177], v[122:125]
	v_mfma_f32_16x16x32_bf16 v[110:113], v[146:149], v[170:173], v[110:113]
	v_mfma_f32_16x16x32_bf16 v[106:109], v[154:157], v[170:173], v[106:109]
	v_mfma_f32_16x16x32_bf16 v[94:97], v[146:149], v[166:169], v[94:97]
	v_mfma_f32_16x16x32_bf16 v[90:93], v[154:157], v[166:169], v[90:93]
	v_mfma_f32_16x16x32_bf16 v[78:81], v[146:149], v[162:165], v[78:81]
	v_mfma_f32_16x16x32_bf16 v[74:77], v[154:157], v[162:165], v[74:77]
	v_mfma_f32_16x16x32_bf16 v[126:129], v[150:153], v[190:193], v[126:129]
	v_mfma_f32_16x16x32_bf16 v[122:125], v[158:161], v[190:193], v[122:125]
	v_mfma_f32_16x16x32_bf16 v[110:113], v[150:153], v[186:189], v[110:113]
	v_mfma_f32_16x16x32_bf16 v[106:109], v[158:161], v[186:189], v[106:109]
	v_mfma_f32_16x16x32_bf16 v[94:97], v[150:153], v[182:185], v[94:97]
	v_mfma_f32_16x16x32_bf16 v[90:93], v[158:161], v[182:185], v[90:93]
	v_mfma_f32_16x16x32_bf16 v[78:81], v[150:153], v[178:181], v[78:81]
	v_mfma_f32_16x16x32_bf16 v[74:77], v[158:161], v[178:181], v[74:77]
	v_mfma_f32_16x16x32_bf16 v[118:121], v[130:133], v[174:177], v[118:121]
	v_mfma_f32_16x16x32_bf16 v[114:117], v[138:141], v[174:177], v[114:117]
	v_mfma_f32_16x16x32_bf16 v[102:105], v[130:133], v[170:173], v[102:105]
	v_mfma_f32_16x16x32_bf16 v[98:101], v[138:141], v[170:173], v[98:101]
	v_mfma_f32_16x16x32_bf16 v[86:89], v[130:133], v[166:169], v[86:89]
	v_mfma_f32_16x16x32_bf16 v[82:85], v[138:141], v[166:169], v[82:85]
	v_mfma_f32_16x16x32_bf16 v[70:73], v[130:133], v[162:165], v[70:73]
	v_mfma_f32_16x16x32_bf16 v[66:69], v[138:141], v[162:165], v[66:69]
	v_mfma_f32_16x16x32_bf16 v[118:121], v[134:137], v[190:193], v[118:121]
	v_mfma_f32_16x16x32_bf16 v[114:117], v[142:145], v[190:193], v[114:117]
	v_mfma_f32_16x16x32_bf16 v[102:105], v[134:137], v[186:189], v[102:105]
	v_mfma_f32_16x16x32_bf16 v[98:101], v[142:145], v[186:189], v[98:101]
	v_mfma_f32_16x16x32_bf16 v[86:89], v[134:137], v[182:185], v[86:89]
	v_mfma_f32_16x16x32_bf16 v[82:85], v[142:145], v[182:185], v[82:85]
	v_mfma_f32_16x16x32_bf16 v[70:73], v[134:137], v[178:181], v[70:73]
	v_mfma_f32_16x16x32_bf16 v[66:69], v[142:145], v[178:181], v[66:69]
	s_add_u32 s60, s56, s58
	s_addc_u32 s61, s57, s59
	s_add_u32 s62, s60, 0x440000
	s_addc_u32 s63, s61, 0
	s_cmp_eq_u32 s58, 0x3fc0000
	s_cselect_b64 s[68:69], -1, 0
	s_and_b64 s[60:61], s[68:69], exec
	s_cselect_b32 s61, s37, s72
	s_cselect_b32 s60, s47, s53
	s_cselect_b32 s63, s1, s63
	s_cselect_b32 s62, s24, s62
	s_barrier
	v_cmp_ne_u32_e64 s[42:43], 1, v233
	s_andn2_b64 vcc, exec, s[44:45]
	s_cbranch_vccnz .LBB0_561
	ds_read_b128 v[174:177], v229 offset:16384
	ds_read_b128 v[190:193], v229 offset:17408
	ds_read_b128 v[170:173], v229 offset:18432
	ds_read_b128 v[186:189], v229 offset:19456
	ds_read_b128 v[166:169], v229 offset:20480
	ds_read_b128 v[182:185], v229 offset:21504
	ds_read_b128 v[162:165], v229 offset:22528
	ds_read_b128 v[178:181], v229 offset:23552
.LBB0_561:
	s_mov_b32 m0, s9
	s_add_u32 s74, s60, 0x4000
	global_load_lds_dwordx4 v194, s[60:61]
	s_mov_b32 m0, s10
	s_addc_u32 s75, s61, 0
	global_load_lds_dwordx4 v196, s[60:61]
	s_mov_b32 m0, s11
	s_and_b64 vcc, exec, s[42:43]
	global_load_lds_dwordx4 v194, s[74:75]
	s_mov_b32 m0, s12
	s_nop 0
	global_load_lds_dwordx4 v196, s[74:75]
	s_mov_b64 s[98:99], s[62:63]
	s_waitcnt vmcnt(6) lgkmcnt(0)
	s_barrier
	s_cbranch_vccnz .LBB0_563
	s_waitcnt lgkmcnt(0)
	v_mfma_f32_16x16x32_bf16 v[62:65], v[146:149], v[174:177], v[62:65]
	v_mfma_f32_16x16x32_bf16 v[58:61], v[154:157], v[174:177], v[58:61]
	v_mfma_f32_16x16x32_bf16 v[46:49], v[146:149], v[170:173], v[46:49]
	v_mfma_f32_16x16x32_bf16 v[42:45], v[154:157], v[170:173], v[42:45]
	v_mfma_f32_16x16x32_bf16 v[30:33], v[146:149], v[166:169], v[30:33]
	v_mfma_f32_16x16x32_bf16 v[26:29], v[154:157], v[166:169], v[26:29]
	v_mfma_f32_16x16x32_bf16 v[14:17], v[146:149], v[162:165], v[14:17]
	v_mfma_f32_16x16x32_bf16 v[10:13], v[154:157], v[162:165], v[10:13]
	v_mfma_f32_16x16x32_bf16 v[62:65], v[150:153], v[190:193], v[62:65]
	v_mfma_f32_16x16x32_bf16 v[58:61], v[158:161], v[190:193], v[58:61]
	v_mfma_f32_16x16x32_bf16 v[46:49], v[150:153], v[186:189], v[46:49]
	v_mfma_f32_16x16x32_bf16 v[42:45], v[158:161], v[186:189], v[42:45]
	v_mfma_f32_16x16x32_bf16 v[30:33], v[150:153], v[182:185], v[30:33]
	v_mfma_f32_16x16x32_bf16 v[26:29], v[158:161], v[182:185], v[26:29]
	v_mfma_f32_16x16x32_bf16 v[14:17], v[150:153], v[178:181], v[14:17]
	v_mfma_f32_16x16x32_bf16 v[10:13], v[158:161], v[178:181], v[10:13]
	v_mfma_f32_16x16x32_bf16 v[54:57], v[130:133], v[174:177], v[54:57]
	v_mfma_f32_16x16x32_bf16 v[50:53], v[138:141], v[174:177], v[50:53]
	v_mfma_f32_16x16x32_bf16 v[38:41], v[130:133], v[170:173], v[38:41]
	v_mfma_f32_16x16x32_bf16 v[34:37], v[138:141], v[170:173], v[34:37]
	v_mfma_f32_16x16x32_bf16 v[22:25], v[130:133], v[166:169], v[22:25]
	v_mfma_f32_16x16x32_bf16 v[18:21], v[138:141], v[166:169], v[18:21]
	v_mfma_f32_16x16x32_bf16 v[6:9], v[130:133], v[162:165], v[6:9]
	v_mfma_f32_16x16x32_bf16 v[2:5], v[138:141], v[162:165], v[2:5]
	v_mfma_f32_16x16x32_bf16 v[54:57], v[134:137], v[190:193], v[54:57]
	v_mfma_f32_16x16x32_bf16 v[50:53], v[142:145], v[190:193], v[50:53]
	v_mfma_f32_16x16x32_bf16 v[38:41], v[134:137], v[186:189], v[38:41]
	v_mfma_f32_16x16x32_bf16 v[34:37], v[142:145], v[186:189], v[34:37]
	v_mfma_f32_16x16x32_bf16 v[22:25], v[134:137], v[182:185], v[22:25]
	v_mfma_f32_16x16x32_bf16 v[18:21], v[142:145], v[182:185], v[18:21]
	v_mfma_f32_16x16x32_bf16 v[6:9], v[134:137], v[178:181], v[6:9]
	v_mfma_f32_16x16x32_bf16 v[2:5], v[142:145], v[178:181], v[2:5]
.LBB0_563:
	s_and_b64 vcc, s[40:41], s[68:69]
	v_cndmask_b32_e64 v131, v215, 0, vcc
	v_cndmask_b32_e32 v130, v214, v198, vcc
	v_lshl_add_u64 v[234:235], s[62:63], 0, v[130:131]
	s_barrier
	s_mov_b32 m0, s8
	s_nop 0
	global_load_lds_dwordx4 v194, s[98:99]
	s_mov_b32 m0, s13
	s_nop 0
	global_load_lds_dwordx4 v196, s[98:99]
	v_add_u32_e32 v130, 0x18000, v226
	v_add_u32_e32 v142, 0x1c000, v226
	ds_read_b128 v[146:149], v130
	ds_read_b128 v[150:153], v130 offset:1024
	ds_read_b128 v[154:157], v130 offset:2048
	ds_read_b128 v[158:161], v130 offset:3072
	ds_read_b128 v[130:133], v142
	ds_read_b128 v[134:137], v142 offset:1024
	ds_read_b128 v[138:141], v142 offset:2048
	ds_read_b128 v[142:145], v142 offset:3072
	s_mov_b32 m0, s14
	v_lshl_add_u64 v[236:237], v[234:235], 0, v[194:195]
	s_waitcnt lgkmcnt(0)
	ds_read_b128 v[174:177], v229 offset:32768
	ds_read_b128 v[190:193], v229 offset:33792
	ds_read_b128 v[170:173], v229 offset:34816
	ds_read_b128 v[186:189], v229 offset:35840
	ds_read_b128 v[166:169], v229 offset:36864
	ds_read_b128 v[182:185], v229 offset:37888
	ds_read_b128 v[162:165], v229 offset:38912
	ds_read_b128 v[178:181], v229 offset:39936
	global_load_lds_dwordx4 v[236:237], off
	v_lshl_add_u64 v[234:235], v[234:235], 0, v[196:197]
	s_mov_b32 m0, s15
	s_nop 0
	global_load_lds_dwordx4 v[234:235], off
	s_waitcnt vmcnt(8) lgkmcnt(0)
	s_barrier
	v_mfma_f32_16x16x32_bf16 v[126:129], v[146:149], v[174:177], v[126:129]
	v_mfma_f32_16x16x32_bf16 v[122:125], v[154:157], v[174:177], v[122:125]
	v_mfma_f32_16x16x32_bf16 v[110:113], v[146:149], v[170:173], v[110:113]
	v_mfma_f32_16x16x32_bf16 v[106:109], v[154:157], v[170:173], v[106:109]
	v_mfma_f32_16x16x32_bf16 v[94:97], v[146:149], v[166:169], v[94:97]
	v_mfma_f32_16x16x32_bf16 v[90:93], v[154:157], v[166:169], v[90:93]
	v_mfma_f32_16x16x32_bf16 v[78:81], v[146:149], v[162:165], v[78:81]
	v_mfma_f32_16x16x32_bf16 v[74:77], v[154:157], v[162:165], v[74:77]
	v_mfma_f32_16x16x32_bf16 v[126:129], v[150:153], v[190:193], v[126:129]
	v_mfma_f32_16x16x32_bf16 v[122:125], v[158:161], v[190:193], v[122:125]
	v_mfma_f32_16x16x32_bf16 v[110:113], v[150:153], v[186:189], v[110:113]
	v_mfma_f32_16x16x32_bf16 v[106:109], v[158:161], v[186:189], v[106:109]
	v_mfma_f32_16x16x32_bf16 v[94:97], v[150:153], v[182:185], v[94:97]
	v_mfma_f32_16x16x32_bf16 v[90:93], v[158:161], v[182:185], v[90:93]
	v_mfma_f32_16x16x32_bf16 v[78:81], v[150:153], v[178:181], v[78:81]
	v_mfma_f32_16x16x32_bf16 v[74:77], v[158:161], v[178:181], v[74:77]
	v_mfma_f32_16x16x32_bf16 v[118:121], v[130:133], v[174:177], v[118:121]
	v_mfma_f32_16x16x32_bf16 v[114:117], v[138:141], v[174:177], v[114:117]
	v_mfma_f32_16x16x32_bf16 v[102:105], v[130:133], v[170:173], v[102:105]
	v_mfma_f32_16x16x32_bf16 v[98:101], v[138:141], v[170:173], v[98:101]
	v_mfma_f32_16x16x32_bf16 v[86:89], v[130:133], v[166:169], v[86:89]
	v_mfma_f32_16x16x32_bf16 v[82:85], v[138:141], v[166:169], v[82:85]
	v_mfma_f32_16x16x32_bf16 v[70:73], v[130:133], v[162:165], v[70:73]
	v_mfma_f32_16x16x32_bf16 v[66:69], v[138:141], v[162:165], v[66:69]
	v_mfma_f32_16x16x32_bf16 v[118:121], v[134:137], v[190:193], v[118:121]
	v_mfma_f32_16x16x32_bf16 v[114:117], v[142:145], v[190:193], v[114:117]
	v_mfma_f32_16x16x32_bf16 v[102:105], v[134:137], v[186:189], v[102:105]
	v_mfma_f32_16x16x32_bf16 v[98:101], v[142:145], v[186:189], v[98:101]
	v_mfma_f32_16x16x32_bf16 v[86:89], v[134:137], v[182:185], v[86:89]
	v_mfma_f32_16x16x32_bf16 v[82:85], v[142:145], v[182:185], v[82:85]
	v_mfma_f32_16x16x32_bf16 v[70:73], v[134:137], v[178:181], v[70:73]
	v_mfma_f32_16x16x32_bf16 v[66:69], v[142:145], v[178:181], v[66:69]
	s_add_u32 s68, s60, 0x40000
	s_addc_u32 s69, s61, 0
	s_add_u32 s62, s62, 0x220000
	s_addc_u32 s63, s63, 0
	s_barrier
	s_and_b64 vcc, exec, s[42:43]
	s_cbranch_vccnz .LBB0_565
	ds_read_b128 v[174:177], v229 offset:49152
	ds_read_b128 v[190:193], v229 offset:50176
	ds_read_b128 v[170:173], v229 offset:51200
	ds_read_b128 v[186:189], v229 offset:52224
	ds_read_b128 v[166:169], v229 offset:53248
	ds_read_b128 v[182:185], v229 offset:54272
	ds_read_b128 v[162:165], v229 offset:55296
	ds_read_b128 v[178:181], v229 offset:56320
.LBB0_565:
	s_mov_b32 m0, s17
	s_add_u32 s60, s60, 0x44000
	global_load_lds_dwordx4 v194, s[68:69]
	s_mov_b32 m0, s54
	s_addc_u32 s61, s61, 0
	global_load_lds_dwordx4 v196, s[68:69]
	s_mov_b32 m0, s70
	s_and_b64 vcc, exec, s[42:43]
	global_load_lds_dwordx4 v194, s[60:61]
	s_mov_b32 m0, s71
	s_nop 0
	global_load_lds_dwordx4 v196, s[60:61]
	s_mov_b64 s[100:101], s[62:63]
	s_waitcnt vmcnt(6) lgkmcnt(0)
	s_barrier
	s_cbranch_vccnz .LBB0_558
	s_waitcnt lgkmcnt(0)
	v_mfma_f32_16x16x32_bf16 v[62:65], v[146:149], v[174:177], v[62:65]
	v_mfma_f32_16x16x32_bf16 v[58:61], v[154:157], v[174:177], v[58:61]
	v_mfma_f32_16x16x32_bf16 v[46:49], v[146:149], v[170:173], v[46:49]
	v_mfma_f32_16x16x32_bf16 v[42:45], v[154:157], v[170:173], v[42:45]
	v_mfma_f32_16x16x32_bf16 v[30:33], v[146:149], v[166:169], v[30:33]
	v_mfma_f32_16x16x32_bf16 v[26:29], v[154:157], v[166:169], v[26:29]
	v_mfma_f32_16x16x32_bf16 v[14:17], v[146:149], v[162:165], v[14:17]
	v_mfma_f32_16x16x32_bf16 v[10:13], v[154:157], v[162:165], v[10:13]
	v_mfma_f32_16x16x32_bf16 v[62:65], v[150:153], v[190:193], v[62:65]
	v_mfma_f32_16x16x32_bf16 v[58:61], v[158:161], v[190:193], v[58:61]
	v_mfma_f32_16x16x32_bf16 v[46:49], v[150:153], v[186:189], v[46:49]
	v_mfma_f32_16x16x32_bf16 v[42:45], v[158:161], v[186:189], v[42:45]
	v_mfma_f32_16x16x32_bf16 v[30:33], v[150:153], v[182:185], v[30:33]
	v_mfma_f32_16x16x32_bf16 v[26:29], v[158:161], v[182:185], v[26:29]
	v_mfma_f32_16x16x32_bf16 v[14:17], v[150:153], v[178:181], v[14:17]
	v_mfma_f32_16x16x32_bf16 v[10:13], v[158:161], v[178:181], v[10:13]
	v_mfma_f32_16x16x32_bf16 v[54:57], v[130:133], v[174:177], v[54:57]
	v_mfma_f32_16x16x32_bf16 v[50:53], v[138:141], v[174:177], v[50:53]
	v_mfma_f32_16x16x32_bf16 v[38:41], v[130:133], v[170:173], v[38:41]
	v_mfma_f32_16x16x32_bf16 v[34:37], v[138:141], v[170:173], v[34:37]
	v_mfma_f32_16x16x32_bf16 v[22:25], v[130:133], v[166:169], v[22:25]
	v_mfma_f32_16x16x32_bf16 v[18:21], v[138:141], v[166:169], v[18:21]
	v_mfma_f32_16x16x32_bf16 v[6:9], v[130:133], v[162:165], v[6:9]
	v_mfma_f32_16x16x32_bf16 v[2:5], v[138:141], v[162:165], v[2:5]
	v_mfma_f32_16x16x32_bf16 v[54:57], v[134:137], v[190:193], v[54:57]
	v_mfma_f32_16x16x32_bf16 v[50:53], v[142:145], v[190:193], v[50:53]
	v_mfma_f32_16x16x32_bf16 v[38:41], v[134:137], v[186:189], v[38:41]
	v_mfma_f32_16x16x32_bf16 v[34:37], v[142:145], v[186:189], v[34:37]
	v_mfma_f32_16x16x32_bf16 v[22:25], v[134:137], v[182:185], v[22:25]
	v_mfma_f32_16x16x32_bf16 v[18:21], v[142:145], v[182:185], v[18:21]
	v_mfma_f32_16x16x32_bf16 v[6:9], v[134:137], v[178:181], v[6:9]
	v_mfma_f32_16x16x32_bf16 v[2:5], v[142:145], v[178:181], v[2:5]
	s_branch .LBB0_558

.LBB0_761:
	s_mov_b32 m0, s14
	s_nop 0
	global_load_lds_dwordx4 v194, s[100:101]
	s_mov_b32 m0, s15
	s_nop 0
	global_load_lds_dwordx4 v196, s[100:101]
	ds_read_b128 v[130:133], v237
	ds_read_b128 v[134:137], v237 offset:1024
	ds_read_b128 v[138:141], v237 offset:2048
	ds_read_b128 v[142:145], v237 offset:3072
	ds_read_b128 v[146:149], v238
	ds_read_b128 v[150:153], v238 offset:1024
	ds_read_b128 v[154:157], v238 offset:2048
	ds_read_b128 v[158:161], v238 offset:3072
	s_add_u32 s48, s0, 0x21c000
	s_addc_u32 s49, s1, 0
	s_cmp_eq_u32 s67, 28
	s_cselect_b32 s42, s55, s62
	s_cselect_b32 s43, s29, s63
	s_cselect_b32 s52, s45, s48
	s_cselect_b32 s53, s31, s49
	s_add_u32 s50, s42, 0xe0000
	s_addc_u32 s51, s43, 0
	s_add_u32 s48, s52, 0x220000
	s_addc_u32 s49, s53, 0
	v_lshl_add_u64 v[208:209], s[0:1], 0, v[202:203]
	s_add_i32 m0, s9, 0xc000
	ds_read_b128 v[162:165], v239
	ds_read_b128 v[166:169], v239 offset:1024
	ds_read_b128 v[170:173], v239 offset:2048
	ds_read_b128 v[174:177], v239 offset:3072
	ds_read_b128 v[178:181], v239 offset:4096
	ds_read_b128 v[182:185], v239 offset:5120
	ds_read_b128 v[186:189], v239 offset:6144
	ds_read_b128 v[190:193], v239 offset:7168
	global_load_lds_dwordx4 v[208:209], off
	v_lshl_add_u64 v[208:209], s[0:1], 0, v[200:201]
	s_add_i32 m0, s9, 0xe000
	s_nop 0
	global_load_lds_dwordx4 v[208:209], off
	s_waitcnt vmcnt(8) lgkmcnt(0)
	s_barrier
	v_mfma_f32_16x16x32_bf16 v[126:129], v[130:133], v[162:165], v[126:129]
	v_mfma_f32_16x16x32_bf16 v[122:125], v[138:141], v[162:165], v[122:125]
	v_mfma_f32_16x16x32_bf16 v[118:121], v[130:133], v[170:173], v[118:121]
	v_mfma_f32_16x16x32_bf16 v[114:117], v[138:141], v[170:173], v[114:117]
	v_mfma_f32_16x16x32_bf16 v[110:113], v[130:133], v[178:181], v[110:113]
	v_mfma_f32_16x16x32_bf16 v[106:109], v[138:141], v[178:181], v[106:109]
	v_mfma_f32_16x16x32_bf16 v[102:105], v[130:133], v[186:189], v[102:105]
	v_mfma_f32_16x16x32_bf16 v[98:101], v[138:141], v[186:189], v[98:101]
	v_mfma_f32_16x16x32_bf16 v[126:129], v[134:137], v[166:169], v[126:129]
	v_mfma_f32_16x16x32_bf16 v[122:125], v[142:145], v[166:169], v[122:125]
	v_mfma_f32_16x16x32_bf16 v[118:121], v[134:137], v[174:177], v[118:121]
	v_mfma_f32_16x16x32_bf16 v[114:117], v[142:145], v[174:177], v[114:117]
	v_mfma_f32_16x16x32_bf16 v[110:113], v[134:137], v[182:185], v[110:113]
	v_mfma_f32_16x16x32_bf16 v[106:109], v[142:145], v[182:185], v[106:109]
	v_mfma_f32_16x16x32_bf16 v[102:105], v[134:137], v[190:193], v[102:105]
	v_mfma_f32_16x16x32_bf16 v[98:101], v[142:145], v[190:193], v[98:101]
	v_mfma_f32_16x16x32_bf16 v[62:65], v[146:149], v[162:165], v[62:65]
	s_add_u32 s60, s52, 0x4000
	s_addc_u32 s61, s53, 0
	v_mfma_f32_16x16x32_bf16 v[58:61], v[154:157], v[162:165], v[58:61]
	v_mfma_f32_16x16x32_bf16 v[54:57], v[146:149], v[170:173], v[54:57]
	v_mfma_f32_16x16x32_bf16 v[50:53], v[154:157], v[170:173], v[50:53]
	v_mfma_f32_16x16x32_bf16 v[46:49], v[146:149], v[178:181], v[46:49]
	v_mfma_f32_16x16x32_bf16 v[42:45], v[154:157], v[178:181], v[42:45]
	v_mfma_f32_16x16x32_bf16 v[38:41], v[146:149], v[186:189], v[38:41]
	v_mfma_f32_16x16x32_bf16 v[34:37], v[154:157], v[186:189], v[34:37]
	v_mfma_f32_16x16x32_bf16 v[62:65], v[150:153], v[166:169], v[62:65]
	v_mfma_f32_16x16x32_bf16 v[58:61], v[158:161], v[166:169], v[58:61]
	v_mfma_f32_16x16x32_bf16 v[54:57], v[150:153], v[174:177], v[54:57]
	v_mfma_f32_16x16x32_bf16 v[50:53], v[158:161], v[174:177], v[50:53]
	v_mfma_f32_16x16x32_bf16 v[46:49], v[150:153], v[182:185], v[46:49]
	v_mfma_f32_16x16x32_bf16 v[42:45], v[158:161], v[182:185], v[42:45]
	v_mfma_f32_16x16x32_bf16 v[38:41], v[150:153], v[190:193], v[38:41]
	v_mfma_f32_16x16x32_bf16 v[34:37], v[158:161], v[190:193], v[34:37]
	s_add_i32 s68, s16, s8
	s_barrier
	s_mov_b32 m0, s68
	ds_read_b128 v[162:165], v239 offset:16384
	ds_read_b128 v[166:169], v239 offset:17408
	ds_read_b128 v[170:173], v239 offset:18432
	ds_read_b128 v[174:177], v239 offset:19456
	ds_read_b128 v[178:181], v239 offset:20480
	ds_read_b128 v[182:185], v239 offset:21504
	ds_read_b128 v[186:189], v239 offset:22528
	ds_read_b128 v[190:193], v239 offset:23552
	global_load_lds_dwordx4 v194, s[42:43]
	s_add_i32 m0, s68, 0x2000
	s_add_u32 s68, s42, 0x4000
	s_addc_u32 s69, s43, 0
	s_add_i32 s70, s17, s8
	global_load_lds_dwordx4 v196, s[42:43]
	s_mov_b32 m0, s70
	s_nop 0
	global_load_lds_dwordx4 v194, s[68:69]
	s_add_i32 m0, s70, 0x2000
	s_nop 0
	global_load_lds_dwordx4 v196, s[68:69]
	s_mov_b64 s[98:99], s[52:53]
	s_waitcnt vmcnt(6) lgkmcnt(0)
	s_barrier
	v_mfma_f32_16x16x32_bf16 v[94:97], v[130:133], v[162:165], v[94:97]
	v_mfma_f32_16x16x32_bf16 v[90:93], v[138:141], v[162:165], v[90:93]
	v_mfma_f32_16x16x32_bf16 v[86:89], v[130:133], v[170:173], v[86:89]
	v_mfma_f32_16x16x32_bf16 v[82:85], v[138:141], v[170:173], v[82:85]
	v_mfma_f32_16x16x32_bf16 v[78:81], v[130:133], v[178:181], v[78:81]
	v_mfma_f32_16x16x32_bf16 v[74:77], v[138:141], v[178:181], v[74:77]
	v_mfma_f32_16x16x32_bf16 v[70:73], v[130:133], v[186:189], v[70:73]
	v_mfma_f32_16x16x32_bf16 v[66:69], v[138:141], v[186:189], v[66:69]
	v_mfma_f32_16x16x32_bf16 v[94:97], v[134:137], v[166:169], v[94:97]
	v_mfma_f32_16x16x32_bf16 v[90:93], v[142:145], v[166:169], v[90:93]
	v_mfma_f32_16x16x32_bf16 v[86:89], v[134:137], v[174:177], v[86:89]
	v_mfma_f32_16x16x32_bf16 v[82:85], v[142:145], v[174:177], v[82:85]
	v_mfma_f32_16x16x32_bf16 v[78:81], v[134:137], v[182:185], v[78:81]
	v_mfma_f32_16x16x32_bf16 v[74:77], v[142:145], v[182:185], v[74:77]
	v_mfma_f32_16x16x32_bf16 v[70:73], v[134:137], v[190:193], v[70:73]
	v_mfma_f32_16x16x32_bf16 v[66:69], v[142:145], v[190:193], v[66:69]
	v_mfma_f32_16x16x32_bf16 v[30:33], v[146:149], v[162:165], v[30:33]
	v_mfma_f32_16x16x32_bf16 v[26:29], v[154:157], v[162:165], v[26:29]
	v_mfma_f32_16x16x32_bf16 v[22:25], v[146:149], v[170:173], v[22:25]
	v_mfma_f32_16x16x32_bf16 v[18:21], v[154:157], v[170:173], v[18:21]
	v_mfma_f32_16x16x32_bf16 v[14:17], v[146:149], v[178:181], v[14:17]
	v_mfma_f32_16x16x32_bf16 v[10:13], v[154:157], v[178:181], v[10:13]
	v_mfma_f32_16x16x32_bf16 v[6:9], v[146:149], v[186:189], v[6:9]
	v_mfma_f32_16x16x32_bf16 v[2:5], v[154:157], v[186:189], v[2:5]
	v_mfma_f32_16x16x32_bf16 v[30:33], v[150:153], v[166:169], v[30:33]
	v_mfma_f32_16x16x32_bf16 v[26:29], v[158:161], v[166:169], v[26:29]
	v_mfma_f32_16x16x32_bf16 v[22:25], v[150:153], v[174:177], v[22:25]
	v_mfma_f32_16x16x32_bf16 v[18:21], v[158:161], v[174:177], v[18:21]
	v_mfma_f32_16x16x32_bf16 v[14:17], v[150:153], v[182:185], v[14:17]
	v_mfma_f32_16x16x32_bf16 v[10:13], v[158:161], v[182:185], v[10:13]
	v_mfma_f32_16x16x32_bf16 v[6:9], v[150:153], v[190:193], v[6:9]
	v_mfma_f32_16x16x32_bf16 v[2:5], v[158:161], v[190:193], v[2:5]
	s_barrier
	s_mov_b32 m0, s9
	s_nop 0
	global_load_lds_dwordx4 v194, s[98:99]
	s_mov_b32 m0, s10
	s_nop 0
	global_load_lds_dwordx4 v196, s[98:99]
	s_add_i32 s52, 0, 0x18000
	s_add_i32 s53, 0, 0x1c000
	v_add_u32_e32 v142, s52, v228
	v_add_u32_e32 v158, s53, v228
	ds_read_b128 v[130:133], v142
	ds_read_b128 v[134:137], v142 offset:1024
	ds_read_b128 v[138:141], v142 offset:2048
	ds_read_b128 v[142:145], v142 offset:3072
	ds_read_b128 v[146:149], v158
	ds_read_b128 v[150:153], v158 offset:1024
	ds_read_b128 v[154:157], v158 offset:2048
	ds_read_b128 v[158:161], v158 offset:3072
	s_mov_b32 m0, s11
	ds_read_b128 v[162:165], v239 offset:32768
	ds_read_b128 v[166:169], v239 offset:33792
	ds_read_b128 v[170:173], v239 offset:34816
	ds_read_b128 v[174:177], v239 offset:35840
	ds_read_b128 v[178:181], v239 offset:36864
	ds_read_b128 v[182:185], v239 offset:37888
	ds_read_b128 v[186:189], v239 offset:38912
	ds_read_b128 v[190:193], v239 offset:39936
	global_load_lds_dwordx4 v194, s[60:61]
	s_mov_b32 m0, s12
	s_nop 0
	global_load_lds_dwordx4 v196, s[60:61]
	s_waitcnt vmcnt(8) lgkmcnt(0)
	s_barrier
	v_mfma_f32_16x16x32_bf16 v[126:129], v[130:133], v[162:165], v[126:129]
	v_mfma_f32_16x16x32_bf16 v[122:125], v[138:141], v[162:165], v[122:125]
	v_mfma_f32_16x16x32_bf16 v[118:121], v[130:133], v[170:173], v[118:121]
	v_mfma_f32_16x16x32_bf16 v[114:117], v[138:141], v[170:173], v[114:117]
	v_mfma_f32_16x16x32_bf16 v[110:113], v[130:133], v[178:181], v[110:113]
	v_mfma_f32_16x16x32_bf16 v[106:109], v[138:141], v[178:181], v[106:109]
	v_mfma_f32_16x16x32_bf16 v[102:105], v[130:133], v[186:189], v[102:105]
	v_mfma_f32_16x16x32_bf16 v[98:101], v[138:141], v[186:189], v[98:101]
	v_mfma_f32_16x16x32_bf16 v[126:129], v[134:137], v[166:169], v[126:129]
	v_mfma_f32_16x16x32_bf16 v[122:125], v[142:145], v[166:169], v[122:125]
	v_mfma_f32_16x16x32_bf16 v[118:121], v[134:137], v[174:177], v[118:121]
	v_mfma_f32_16x16x32_bf16 v[114:117], v[142:145], v[174:177], v[114:117]
	v_mfma_f32_16x16x32_bf16 v[110:113], v[134:137], v[182:185], v[110:113]
	v_mfma_f32_16x16x32_bf16 v[106:109], v[142:145], v[182:185], v[106:109]
	v_mfma_f32_16x16x32_bf16 v[102:105], v[134:137], v[190:193], v[102:105]
	v_mfma_f32_16x16x32_bf16 v[98:101], v[142:145], v[190:193], v[98:101]
	v_mfma_f32_16x16x32_bf16 v[62:65], v[146:149], v[162:165], v[62:65]
	v_mfma_f32_16x16x32_bf16 v[58:61], v[154:157], v[162:165], v[58:61]
	v_mfma_f32_16x16x32_bf16 v[54:57], v[146:149], v[170:173], v[54:57]
	v_mfma_f32_16x16x32_bf16 v[50:53], v[154:157], v[170:173], v[50:53]
	v_mfma_f32_16x16x32_bf16 v[46:49], v[146:149], v[178:181], v[46:49]
	v_mfma_f32_16x16x32_bf16 v[42:45], v[154:157], v[178:181], v[42:45]
	v_mfma_f32_16x16x32_bf16 v[38:41], v[146:149], v[186:189], v[38:41]
	v_mfma_f32_16x16x32_bf16 v[34:37], v[154:157], v[186:189], v[34:37]
	v_mfma_f32_16x16x32_bf16 v[62:65], v[150:153], v[166:169], v[62:65]
	v_mfma_f32_16x16x32_bf16 v[58:61], v[158:161], v[166:169], v[58:61]
	v_mfma_f32_16x16x32_bf16 v[54:57], v[150:153], v[174:177], v[54:57]
	v_mfma_f32_16x16x32_bf16 v[50:53], v[158:161], v[174:177], v[50:53]
	v_mfma_f32_16x16x32_bf16 v[46:49], v[150:153], v[182:185], v[46:49]
	v_mfma_f32_16x16x32_bf16 v[42:45], v[158:161], v[182:185], v[42:45]
	v_mfma_f32_16x16x32_bf16 v[38:41], v[150:153], v[190:193], v[38:41]
	v_mfma_f32_16x16x32_bf16 v[34:37], v[158:161], v[190:193], v[34:37]
	s_add_i32 s52, s52, s8
	s_barrier
	s_mov_b32 m0, s52
	ds_read_b128 v[162:165], v239 offset:49152
	ds_read_b128 v[166:169], v239 offset:50176
	ds_read_b128 v[170:173], v239 offset:51200
	ds_read_b128 v[174:177], v239 offset:52224
	ds_read_b128 v[178:181], v239 offset:53248
	ds_read_b128 v[182:185], v239 offset:54272
	ds_read_b128 v[186:189], v239 offset:55296
	ds_read_b128 v[190:193], v239 offset:56320
	global_load_lds_dwordx4 v194, s[50:51]
	s_add_i32 m0, s52, 0x2000
	s_add_u32 s42, s42, 0xe4000
	v_lshl_add_u64 v[208:209], s[50:51], 0, v[196:197]
	s_addc_u32 s43, s43, 0
	s_add_i32 s50, s53, s8
	global_load_lds_dwordx4 v[208:209], off
	s_mov_b32 m0, s50
	s_nop 0
	global_load_lds_dwordx4 v194, s[42:43]
	s_add_i32 m0, s50, 0x2000
	s_nop 0
	global_load_lds_dwordx4 v196, s[42:43]
	s_mov_b64 s[100:101], s[48:49]
	s_waitcnt vmcnt(6) lgkmcnt(0)
	s_barrier
	v_mfma_f32_16x16x32_bf16 v[94:97], v[130:133], v[162:165], v[94:97]
	v_mfma_f32_16x16x32_bf16 v[90:93], v[138:141], v[162:165], v[90:93]
	v_mfma_f32_16x16x32_bf16 v[86:89], v[130:133], v[170:173], v[86:89]
	v_mfma_f32_16x16x32_bf16 v[82:85], v[138:141], v[170:173], v[82:85]
	v_mfma_f32_16x16x32_bf16 v[78:81], v[130:133], v[178:181], v[78:81]
	v_mfma_f32_16x16x32_bf16 v[74:77], v[138:141], v[178:181], v[74:77]
	v_mfma_f32_16x16x32_bf16 v[70:73], v[130:133], v[186:189], v[70:73]
	v_mfma_f32_16x16x32_bf16 v[66:69], v[138:141], v[186:189], v[66:69]
	v_mfma_f32_16x16x32_bf16 v[94:97], v[134:137], v[166:169], v[94:97]
	v_mfma_f32_16x16x32_bf16 v[90:93], v[142:145], v[166:169], v[90:93]
	v_mfma_f32_16x16x32_bf16 v[86:89], v[134:137], v[174:177], v[86:89]
	v_mfma_f32_16x16x32_bf16 v[82:85], v[142:145], v[174:177], v[82:85]
	v_mfma_f32_16x16x32_bf16 v[78:81], v[134:137], v[182:185], v[78:81]
	v_mfma_f32_16x16x32_bf16 v[74:77], v[142:145], v[182:185], v[74:77]
	v_mfma_f32_16x16x32_bf16 v[70:73], v[134:137], v[190:193], v[70:73]
	v_mfma_f32_16x16x32_bf16 v[66:69], v[142:145], v[190:193], v[66:69]
	v_mfma_f32_16x16x32_bf16 v[30:33], v[146:149], v[162:165], v[30:33]
	v_mfma_f32_16x16x32_bf16 v[26:29], v[154:157], v[162:165], v[26:29]
	v_mfma_f32_16x16x32_bf16 v[22:25], v[146:149], v[170:173], v[22:25]
	v_mfma_f32_16x16x32_bf16 v[18:21], v[154:157], v[170:173], v[18:21]
	v_mfma_f32_16x16x32_bf16 v[14:17], v[146:149], v[178:181], v[14:17]
	v_mfma_f32_16x16x32_bf16 v[10:13], v[154:157], v[178:181], v[10:13]
	v_mfma_f32_16x16x32_bf16 v[6:9], v[146:149], v[186:189], v[6:9]
	v_mfma_f32_16x16x32_bf16 v[2:5], v[154:157], v[186:189], v[2:5]
	v_mfma_f32_16x16x32_bf16 v[30:33], v[150:153], v[166:169], v[30:33]
	v_mfma_f32_16x16x32_bf16 v[26:29], v[158:161], v[166:169], v[26:29]
	v_mfma_f32_16x16x32_bf16 v[22:25], v[150:153], v[174:177], v[22:25]
	v_mfma_f32_16x16x32_bf16 v[18:21], v[158:161], v[174:177], v[18:21]
	v_mfma_f32_16x16x32_bf16 v[14:17], v[150:153], v[182:185], v[14:17]
	v_mfma_f32_16x16x32_bf16 v[10:13], v[158:161], v[182:185], v[10:13]
	v_mfma_f32_16x16x32_bf16 v[6:9], v[150:153], v[190:193], v[6:9]
	v_mfma_f32_16x16x32_bf16 v[2:5], v[158:161], v[190:193], v[2:5]
	s_add_i32 s67, s67, 2
	s_add_u32 s62, s62, 0x1c0000
	s_addc_u32 s63, s63, 0
	s_add_u32 s0, s0, 0x440000
	s_addc_u32 s1, s1, 0
	s_cmp_gt_u32 s67, 29
	s_barrier
	s_cbranch_scc0 .LBB0_761
	s_and_b64 vcc, exec, s[26:27]
	s_cbranch_vccz .LBB0_764
	s_barrier

.LBB0_902:
	s_add_i32 s78, s78, 2
	s_add_u32 s76, s76, 0x1c0000
	s_addc_u32 s77, s77, 0
	s_add_u32 s62, s62, 0x440000
	s_addc_u32 s63, s63, 0
	s_cmp_gt_u32 s78, 29
	s_barrier
	s_cbranch_scc1 .LBB0_911
.LBB0_903:
	s_mov_b32 m0, s23
	s_nop 0
	global_load_lds_dwordx4 v194, s[100:101]
	s_mov_b32 m0, s31
	s_nop 0
	global_load_lds_dwordx4 v196, s[100:101]
	ds_read_b128 v[146:149], v225
	ds_read_b128 v[150:153], v225 offset:1024
	ds_read_b128 v[154:157], v225 offset:2048
	ds_read_b128 v[158:161], v225 offset:3072
	ds_read_b128 v[130:133], v227
	ds_read_b128 v[134:137], v227 offset:1024
	ds_read_b128 v[138:141], v227 offset:2048
	ds_read_b128 v[142:145], v227 offset:3072
	v_lshl_add_u64 v[234:235], v[210:211], 0, s[62:63]
	s_add_i32 m0, s8, 0xc000
	s_waitcnt lgkmcnt(0)
	ds_read_b128 v[174:177], v228
	ds_read_b128 v[190:193], v228 offset:1024
	ds_read_b128 v[170:173], v228 offset:2048
	ds_read_b128 v[186:189], v228 offset:3072
	ds_read_b128 v[166:169], v228 offset:4096
	ds_read_b128 v[182:185], v228 offset:5120
	ds_read_b128 v[162:165], v228 offset:6144
	ds_read_b128 v[178:181], v228 offset:7168
	global_load_lds_dwordx4 v[234:235], off
	v_lshl_add_u64 v[234:235], v[212:213], 0, s[62:63]
	s_add_i32 m0, s8, 0xe000
	s_nop 0
	global_load_lds_dwordx4 v[234:235], off
	s_waitcnt vmcnt(8) lgkmcnt(0)
	s_barrier
	v_mfma_f32_16x16x32_bf16 v[126:129], v[146:149], v[174:177], v[126:129]
	v_mfma_f32_16x16x32_bf16 v[122:125], v[154:157], v[174:177], v[122:125]
	v_mfma_f32_16x16x32_bf16 v[118:121], v[146:149], v[170:173], v[118:121]
	v_mfma_f32_16x16x32_bf16 v[114:117], v[154:157], v[170:173], v[114:117]
	v_mfma_f32_16x16x32_bf16 v[110:113], v[146:149], v[166:169], v[110:113]
	v_mfma_f32_16x16x32_bf16 v[106:109], v[154:157], v[166:169], v[106:109]
	v_mfma_f32_16x16x32_bf16 v[102:105], v[146:149], v[162:165], v[102:105]
	v_mfma_f32_16x16x32_bf16 v[98:101], v[154:157], v[162:165], v[98:101]
	v_mfma_f32_16x16x32_bf16 v[126:129], v[150:153], v[190:193], v[126:129]
	v_mfma_f32_16x16x32_bf16 v[122:125], v[158:161], v[190:193], v[122:125]
	v_mfma_f32_16x16x32_bf16 v[118:121], v[150:153], v[186:189], v[118:121]
	v_mfma_f32_16x16x32_bf16 v[114:117], v[158:161], v[186:189], v[114:117]
	v_mfma_f32_16x16x32_bf16 v[110:113], v[150:153], v[182:185], v[110:113]
	v_mfma_f32_16x16x32_bf16 v[106:109], v[158:161], v[182:185], v[106:109]
	v_mfma_f32_16x16x32_bf16 v[102:105], v[150:153], v[178:181], v[102:105]
	v_mfma_f32_16x16x32_bf16 v[98:101], v[158:161], v[178:181], v[98:101]
	v_mfma_f32_16x16x32_bf16 v[94:97], v[130:133], v[174:177], v[94:97]
	v_mfma_f32_16x16x32_bf16 v[90:93], v[138:141], v[174:177], v[90:93]
	v_mfma_f32_16x16x32_bf16 v[86:89], v[130:133], v[170:173], v[86:89]
	v_mfma_f32_16x16x32_bf16 v[82:85], v[138:141], v[170:173], v[82:85]
	v_mfma_f32_16x16x32_bf16 v[78:81], v[130:133], v[166:169], v[78:81]
	v_mfma_f32_16x16x32_bf16 v[74:77], v[138:141], v[166:169], v[74:77]
	v_mfma_f32_16x16x32_bf16 v[70:73], v[130:133], v[162:165], v[70:73]
	v_mfma_f32_16x16x32_bf16 v[66:69], v[138:141], v[162:165], v[66:69]
	v_mfma_f32_16x16x32_bf16 v[94:97], v[134:137], v[190:193], v[94:97]
	v_mfma_f32_16x16x32_bf16 v[90:93], v[142:145], v[190:193], v[90:93]
	v_mfma_f32_16x16x32_bf16 v[86:89], v[134:137], v[186:189], v[86:89]
	v_mfma_f32_16x16x32_bf16 v[82:85], v[142:145], v[186:189], v[82:85]
	v_mfma_f32_16x16x32_bf16 v[78:81], v[134:137], v[182:185], v[78:81]
	v_mfma_f32_16x16x32_bf16 v[74:77], v[142:145], v[182:185], v[74:77]
	v_mfma_f32_16x16x32_bf16 v[70:73], v[134:137], v[178:181], v[70:73]
	v_mfma_f32_16x16x32_bf16 v[66:69], v[142:145], v[178:181], v[66:69]
	s_add_u32 s68, s0, s62
	s_addc_u32 s69, s1, s63
	s_add_u32 s70, s68, 0x440000
	s_addc_u32 s71, s69, 0
	s_cmp_eq_u32 s62, 0x3fc0000
	s_cselect_b64 s[72:73], -1, 0
	s_and_b64 s[68:69], s[72:73], exec
	s_cselect_b32 s69, s37, s77
	s_cselect_b32 s68, s75, s76
	s_cselect_b32 s71, s35, s71
	s_cselect_b32 s70, s74, s70
	s_barrier
	v_cmp_ne_u32_e64 s[42:43], 1, v233
	s_andn2_b64 vcc, exec, s[44:45]
	s_cbranch_vccnz .LBB0_905
	ds_read_b128 v[174:177], v228 offset:16384
	ds_read_b128 v[190:193], v228 offset:17408
	ds_read_b128 v[170:173], v228 offset:18432
	ds_read_b128 v[186:189], v228 offset:19456
	ds_read_b128 v[166:169], v228 offset:20480
	ds_read_b128 v[182:185], v228 offset:21504
	ds_read_b128 v[162:165], v228 offset:22528
	ds_read_b128 v[178:181], v228 offset:23552
.LBB0_905:
	s_mov_b32 m0, s9
	s_add_u32 s80, s68, 0x4000
	global_load_lds_dwordx4 v194, s[68:69]
	s_mov_b32 m0, s10
	s_addc_u32 s81, s69, 0
	global_load_lds_dwordx4 v196, s[68:69]
	s_mov_b32 m0, s11
	s_and_b64 vcc, exec, s[42:43]
	global_load_lds_dwordx4 v194, s[80:81]
	s_mov_b32 m0, s12
	s_nop 0
	global_load_lds_dwordx4 v196, s[80:81]
	s_mov_b64 s[98:99], s[70:71]
	s_waitcnt vmcnt(6) lgkmcnt(0)
	s_barrier
	s_cbranch_vccnz .LBB0_907
	s_waitcnt lgkmcnt(0)
	v_mfma_f32_16x16x32_bf16 v[62:65], v[146:149], v[174:177], v[62:65]
	v_mfma_f32_16x16x32_bf16 v[58:61], v[154:157], v[174:177], v[58:61]
	v_mfma_f32_16x16x32_bf16 v[54:57], v[146:149], v[170:173], v[54:57]
	v_mfma_f32_16x16x32_bf16 v[50:53], v[154:157], v[170:173], v[50:53]
	v_mfma_f32_16x16x32_bf16 v[46:49], v[146:149], v[166:169], v[46:49]
	v_mfma_f32_16x16x32_bf16 v[42:45], v[154:157], v[166:169], v[42:45]
	v_mfma_f32_16x16x32_bf16 v[38:41], v[146:149], v[162:165], v[38:41]
	v_mfma_f32_16x16x32_bf16 v[34:37], v[154:157], v[162:165], v[34:37]
	v_mfma_f32_16x16x32_bf16 v[62:65], v[150:153], v[190:193], v[62:65]
	v_mfma_f32_16x16x32_bf16 v[58:61], v[158:161], v[190:193], v[58:61]
	v_mfma_f32_16x16x32_bf16 v[54:57], v[150:153], v[186:189], v[54:57]
	v_mfma_f32_16x16x32_bf16 v[50:53], v[158:161], v[186:189], v[50:53]
	v_mfma_f32_16x16x32_bf16 v[46:49], v[150:153], v[182:185], v[46:49]
	v_mfma_f32_16x16x32_bf16 v[42:45], v[158:161], v[182:185], v[42:45]
	v_mfma_f32_16x16x32_bf16 v[38:41], v[150:153], v[178:181], v[38:41]
	v_mfma_f32_16x16x32_bf16 v[34:37], v[158:161], v[178:181], v[34:37]
	v_mfma_f32_16x16x32_bf16 v[30:33], v[130:133], v[174:177], v[30:33]
	v_mfma_f32_16x16x32_bf16 v[26:29], v[138:141], v[174:177], v[26:29]
	v_mfma_f32_16x16x32_bf16 v[22:25], v[130:133], v[170:173], v[22:25]
	v_mfma_f32_16x16x32_bf16 v[18:21], v[138:141], v[170:173], v[18:21]
	v_mfma_f32_16x16x32_bf16 v[14:17], v[130:133], v[166:169], v[14:17]
	v_mfma_f32_16x16x32_bf16 v[10:13], v[138:141], v[166:169], v[10:13]
	v_mfma_f32_16x16x32_bf16 v[6:9], v[130:133], v[162:165], v[6:9]
	v_mfma_f32_16x16x32_bf16 v[2:5], v[138:141], v[162:165], v[2:5]
	v_mfma_f32_16x16x32_bf16 v[30:33], v[134:137], v[190:193], v[30:33]
	v_mfma_f32_16x16x32_bf16 v[26:29], v[142:145], v[190:193], v[26:29]
	v_mfma_f32_16x16x32_bf16 v[22:25], v[134:137], v[186:189], v[22:25]
	v_mfma_f32_16x16x32_bf16 v[18:21], v[142:145], v[186:189], v[18:21]
	v_mfma_f32_16x16x32_bf16 v[14:17], v[134:137], v[182:185], v[14:17]
	v_mfma_f32_16x16x32_bf16 v[10:13], v[142:145], v[182:185], v[10:13]
	v_mfma_f32_16x16x32_bf16 v[6:9], v[134:137], v[178:181], v[6:9]
	v_mfma_f32_16x16x32_bf16 v[2:5], v[142:145], v[178:181], v[2:5]
.LBB0_907:
	s_and_b64 vcc, s[40:41], s[72:73]
	v_cndmask_b32_e64 v131, v209, 0, vcc
	v_cndmask_b32_e32 v130, v208, v198, vcc
	v_lshl_add_u64 v[234:235], s[70:71], 0, v[130:131]
	s_barrier
	s_mov_b32 m0, s8
	s_nop 0
	global_load_lds_dwordx4 v194, s[98:99]
	s_mov_b32 m0, s13
	s_nop 0
	global_load_lds_dwordx4 v196, s[98:99]
	v_add_u32_e32 v130, 0x18000, v224
	v_add_u32_e32 v142, 0x1c000, v224
	ds_read_b128 v[146:149], v130
	ds_read_b128 v[150:153], v130 offset:1024
	ds_read_b128 v[154:157], v130 offset:2048
	ds_read_b128 v[158:161], v130 offset:3072
	ds_read_b128 v[130:133], v142
	ds_read_b128 v[134:137], v142 offset:1024
	ds_read_b128 v[138:141], v142 offset:2048
	ds_read_b128 v[142:145], v142 offset:3072
	s_mov_b32 m0, s14
	v_lshl_add_u64 v[236:237], v[234:235], 0, v[194:195]
	s_waitcnt lgkmcnt(0)
	ds_read_b128 v[174:177], v228 offset:32768
	ds_read_b128 v[190:193], v228 offset:33792
	ds_read_b128 v[170:173], v228 offset:34816
	ds_read_b128 v[186:189], v228 offset:35840
	ds_read_b128 v[166:169], v228 offset:36864
	ds_read_b128 v[182:185], v228 offset:37888
	ds_read_b128 v[162:165], v228 offset:38912
	ds_read_b128 v[178:181], v228 offset:39936
	global_load_lds_dwordx4 v[236:237], off
	v_lshl_add_u64 v[234:235], v[234:235], 0, v[196:197]
	s_mov_b32 m0, s15
	s_nop 0
	global_load_lds_dwordx4 v[234:235], off
	s_waitcnt vmcnt(8) lgkmcnt(0)
	s_barrier
	v_mfma_f32_16x16x32_bf16 v[126:129], v[146:149], v[174:177], v[126:129]
	v_mfma_f32_16x16x32_bf16 v[122:125], v[154:157], v[174:177], v[122:125]
	v_mfma_f32_16x16x32_bf16 v[118:121], v[146:149], v[170:173], v[118:121]
	v_mfma_f32_16x16x32_bf16 v[114:117], v[154:157], v[170:173], v[114:117]
	v_mfma_f32_16x16x32_bf16 v[110:113], v[146:149], v[166:169], v[110:113]
	v_mfma_f32_16x16x32_bf16 v[106:109], v[154:157], v[166:169], v[106:109]
	v_mfma_f32_16x16x32_bf16 v[102:105], v[146:149], v[162:165], v[102:105]
	v_mfma_f32_16x16x32_bf16 v[98:101], v[154:157], v[162:165], v[98:101]
	v_mfma_f32_16x16x32_bf16 v[126:129], v[150:153], v[190:193], v[126:129]
	v_mfma_f32_16x16x32_bf16 v[122:125], v[158:161], v[190:193], v[122:125]
	v_mfma_f32_16x16x32_bf16 v[118:121], v[150:153], v[186:189], v[118:121]
	v_mfma_f32_16x16x32_bf16 v[114:117], v[158:161], v[186:189], v[114:117]
	v_mfma_f32_16x16x32_bf16 v[110:113], v[150:153], v[182:185], v[110:113]
	v_mfma_f32_16x16x32_bf16 v[106:109], v[158:161], v[182:185], v[106:109]
	v_mfma_f32_16x16x32_bf16 v[102:105], v[150:153], v[178:181], v[102:105]
	v_mfma_f32_16x16x32_bf16 v[98:101], v[158:161], v[178:181], v[98:101]
	v_mfma_f32_16x16x32_bf16 v[94:97], v[130:133], v[174:177], v[94:97]
	v_mfma_f32_16x16x32_bf16 v[90:93], v[138:141], v[174:177], v[90:93]
	v_mfma_f32_16x16x32_bf16 v[86:89], v[130:133], v[170:173], v[86:89]
	v_mfma_f32_16x16x32_bf16 v[82:85], v[138:141], v[170:173], v[82:85]
	v_mfma_f32_16x16x32_bf16 v[78:81], v[130:133], v[166:169], v[78:81]
	v_mfma_f32_16x16x32_bf16 v[74:77], v[138:141], v[166:169], v[74:77]
	v_mfma_f32_16x16x32_bf16 v[70:73], v[130:133], v[162:165], v[70:73]
	v_mfma_f32_16x16x32_bf16 v[66:69], v[138:141], v[162:165], v[66:69]
	v_mfma_f32_16x16x32_bf16 v[94:97], v[134:137], v[190:193], v[94:97]
	v_mfma_f32_16x16x32_bf16 v[90:93], v[142:145], v[190:193], v[90:93]
	v_mfma_f32_16x16x32_bf16 v[86:89], v[134:137], v[186:189], v[86:89]
	v_mfma_f32_16x16x32_bf16 v[82:85], v[142:145], v[186:189], v[82:85]
	v_mfma_f32_16x16x32_bf16 v[78:81], v[134:137], v[182:185], v[78:81]
	v_mfma_f32_16x16x32_bf16 v[74:77], v[142:145], v[182:185], v[74:77]
	v_mfma_f32_16x16x32_bf16 v[70:73], v[134:137], v[178:181], v[70:73]
	v_mfma_f32_16x16x32_bf16 v[66:69], v[142:145], v[178:181], v[66:69]
	s_add_u32 s72, s68, 0xe0000
	s_addc_u32 s73, s69, 0
	s_add_u32 s70, s70, 0x220000
	s_addc_u32 s71, s71, 0
	s_barrier
	s_and_b64 vcc, exec, s[42:43]
	s_cbranch_vccnz .LBB0_909
	ds_read_b128 v[174:177], v228 offset:49152
	ds_read_b128 v[190:193], v228 offset:50176
	ds_read_b128 v[170:173], v228 offset:51200
	ds_read_b128 v[186:189], v228 offset:52224
	ds_read_b128 v[166:169], v228 offset:53248
	ds_read_b128 v[182:185], v228 offset:54272
	ds_read_b128 v[162:165], v228 offset:55296
	ds_read_b128 v[178:181], v228 offset:56320
.LBB0_909:
	s_mov_b32 m0, s16
	s_add_u32 s68, s68, 0xe4000
	global_load_lds_dwordx4 v194, s[72:73]
	s_mov_b32 m0, s17
	s_addc_u32 s69, s69, 0
	global_load_lds_dwordx4 v196, s[72:73]
	s_mov_b32 m0, s54
	s_and_b64 vcc, exec, s[42:43]
	global_load_lds_dwordx4 v194, s[68:69]
	s_mov_b32 m0, s55
	s_nop 0
	global_load_lds_dwordx4 v196, s[68:69]
	s_mov_b64 s[100:101], s[70:71]
	s_waitcnt vmcnt(6) lgkmcnt(0)
	s_barrier
	s_cbranch_vccnz .LBB0_902
	s_waitcnt lgkmcnt(0)
	v_mfma_f32_16x16x32_bf16 v[62:65], v[146:149], v[174:177], v[62:65]
	v_mfma_f32_16x16x32_bf16 v[58:61], v[154:157], v[174:177], v[58:61]
	v_mfma_f32_16x16x32_bf16 v[54:57], v[146:149], v[170:173], v[54:57]
	v_mfma_f32_16x16x32_bf16 v[50:53], v[154:157], v[170:173], v[50:53]
	v_mfma_f32_16x16x32_bf16 v[46:49], v[146:149], v[166:169], v[46:49]
	v_mfma_f32_16x16x32_bf16 v[42:45], v[154:157], v[166:169], v[42:45]
	v_mfma_f32_16x16x32_bf16 v[38:41], v[146:149], v[162:165], v[38:41]
	v_mfma_f32_16x16x32_bf16 v[34:37], v[154:157], v[162:165], v[34:37]
	v_mfma_f32_16x16x32_bf16 v[62:65], v[150:153], v[190:193], v[62:65]
	v_mfma_f32_16x16x32_bf16 v[58:61], v[158:161], v[190:193], v[58:61]
	v_mfma_f32_16x16x32_bf16 v[54:57], v[150:153], v[186:189], v[54:57]
	v_mfma_f32_16x16x32_bf16 v[50:53], v[158:161], v[186:189], v[50:53]
	v_mfma_f32_16x16x32_bf16 v[46:49], v[150:153], v[182:185], v[46:49]
	v_mfma_f32_16x16x32_bf16 v[42:45], v[158:161], v[182:185], v[42:45]
	v_mfma_f32_16x16x32_bf16 v[38:41], v[150:153], v[178:181], v[38:41]
	v_mfma_f32_16x16x32_bf16 v[34:37], v[158:161], v[178:181], v[34:37]
	v_mfma_f32_16x16x32_bf16 v[30:33], v[130:133], v[174:177], v[30:33]
	v_mfma_f32_16x16x32_bf16 v[26:29], v[138:141], v[174:177], v[26:29]
	v_mfma_f32_16x16x32_bf16 v[22:25], v[130:133], v[170:173], v[22:25]
	v_mfma_f32_16x16x32_bf16 v[18:21], v[138:141], v[170:173], v[18:21]
	v_mfma_f32_16x16x32_bf16 v[14:17], v[130:133], v[166:169], v[14:17]
	v_mfma_f32_16x16x32_bf16 v[10:13], v[138:141], v[166:169], v[10:13]
	v_mfma_f32_16x16x32_bf16 v[6:9], v[130:133], v[162:165], v[6:9]
	v_mfma_f32_16x16x32_bf16 v[2:5], v[138:141], v[162:165], v[2:5]
	v_mfma_f32_16x16x32_bf16 v[30:33], v[134:137], v[190:193], v[30:33]
	v_mfma_f32_16x16x32_bf16 v[26:29], v[142:145], v[190:193], v[26:29]
	v_mfma_f32_16x16x32_bf16 v[22:25], v[134:137], v[186:189], v[22:25]
	v_mfma_f32_16x16x32_bf16 v[18:21], v[142:145], v[186:189], v[18:21]
	v_mfma_f32_16x16x32_bf16 v[14:17], v[134:137], v[182:185], v[14:17]
	v_mfma_f32_16x16x32_bf16 v[10:13], v[142:145], v[182:185], v[10:13]
	v_mfma_f32_16x16x32_bf16 v[6:9], v[134:137], v[178:181], v[6:9]
	v_mfma_f32_16x16x32_bf16 v[2:5], v[142:145], v[178:181], v[2:5]
	s_branch .LBB0_902

.LBB0_1288:
	s_add_i32 s67, s67, 2
	s_add_u32 s62, s62, 0x80000
	s_addc_u32 s63, s63, 0
	s_add_u32 s48, s48, 0x440000
	s_addc_u32 s49, s49, 0
	s_cmp_gt_u32 s67, 29
	s_barrier
	s_cbranch_scc1 .LBB0_1297
.LBB0_1289:
	s_mov_b32 m0, s27
	s_nop 0
	global_load_lds_dwordx4 v194, s[100:101]
	s_mov_b32 m0, s54
	s_nop 0
	global_load_lds_dwordx4 v196, s[100:101]
	v_add_u32_e32 v142, 0x14000, v229
	ds_read_b128 v[146:149], v230
	ds_read_b128 v[150:153], v230 offset:1024
	ds_read_b128 v[154:157], v230 offset:2048
	ds_read_b128 v[158:161], v230 offset:3072
	ds_read_b128 v[130:133], v142
	ds_read_b128 v[134:137], v142 offset:1024
	ds_read_b128 v[138:141], v142 offset:2048
	ds_read_b128 v[142:145], v142 offset:3072
	v_lshl_add_u64 v[234:235], v[222:223], 0, s[48:49]
	s_add_i32 m0, s8, 0xc000
	s_waitcnt lgkmcnt(0)
	ds_read_b128 v[174:177], v231
	ds_read_b128 v[190:193], v231 offset:1024
	ds_read_b128 v[170:173], v231 offset:2048
	ds_read_b128 v[186:189], v231 offset:3072
	ds_read_b128 v[166:169], v231 offset:4096
	ds_read_b128 v[182:185], v231 offset:5120
	ds_read_b128 v[162:165], v231 offset:6144
	ds_read_b128 v[178:181], v231 offset:7168
	global_load_lds_dwordx4 v[234:235], off
	v_lshl_add_u64 v[234:235], v[224:225], 0, s[48:49]
	s_add_i32 m0, s8, 0xe000
	s_nop 0
	global_load_lds_dwordx4 v[234:235], off
	s_waitcnt vmcnt(8) lgkmcnt(0)
	s_barrier
	v_mfma_f32_16x16x32_bf16 v[126:129], v[146:149], v[174:177], v[126:129]
	v_mfma_f32_16x16x32_bf16 v[122:125], v[154:157], v[174:177], v[122:125]
	v_mfma_f32_16x16x32_bf16 v[118:121], v[146:149], v[170:173], v[118:121]
	v_mfma_f32_16x16x32_bf16 v[110:113], v[154:157], v[170:173], v[110:113]
	v_mfma_f32_16x16x32_bf16 v[102:105], v[146:149], v[166:169], v[102:105]
	v_mfma_f32_16x16x32_bf16 v[94:97], v[154:157], v[166:169], v[94:97]
	v_mfma_f32_16x16x32_bf16 v[86:89], v[146:149], v[162:165], v[86:89]
	v_mfma_f32_16x16x32_bf16 v[78:81], v[154:157], v[162:165], v[78:81]
	v_mfma_f32_16x16x32_bf16 v[126:129], v[150:153], v[190:193], v[126:129]
	v_mfma_f32_16x16x32_bf16 v[122:125], v[158:161], v[190:193], v[122:125]
	v_mfma_f32_16x16x32_bf16 v[118:121], v[150:153], v[186:189], v[118:121]
	v_mfma_f32_16x16x32_bf16 v[110:113], v[158:161], v[186:189], v[110:113]
	v_mfma_f32_16x16x32_bf16 v[102:105], v[150:153], v[182:185], v[102:105]
	v_mfma_f32_16x16x32_bf16 v[94:97], v[158:161], v[182:185], v[94:97]
	v_mfma_f32_16x16x32_bf16 v[86:89], v[150:153], v[178:181], v[86:89]
	v_mfma_f32_16x16x32_bf16 v[78:81], v[158:161], v[178:181], v[78:81]
	v_mfma_f32_16x16x32_bf16 v[114:117], v[130:133], v[174:177], v[114:117]
	v_mfma_f32_16x16x32_bf16 v[106:109], v[138:141], v[174:177], v[106:109]
	v_mfma_f32_16x16x32_bf16 v[98:101], v[130:133], v[170:173], v[98:101]
	v_mfma_f32_16x16x32_bf16 v[90:93], v[138:141], v[170:173], v[90:93]
	v_mfma_f32_16x16x32_bf16 v[82:85], v[130:133], v[166:169], v[82:85]
	v_mfma_f32_16x16x32_bf16 v[74:77], v[138:141], v[166:169], v[74:77]
	v_mfma_f32_16x16x32_bf16 v[70:73], v[130:133], v[162:165], v[70:73]
	v_mfma_f32_16x16x32_bf16 v[66:69], v[138:141], v[162:165], v[66:69]
	v_mfma_f32_16x16x32_bf16 v[114:117], v[134:137], v[190:193], v[114:117]
	v_mfma_f32_16x16x32_bf16 v[106:109], v[142:145], v[190:193], v[106:109]
	v_mfma_f32_16x16x32_bf16 v[98:101], v[134:137], v[186:189], v[98:101]
	v_mfma_f32_16x16x32_bf16 v[90:93], v[142:145], v[186:189], v[90:93]
	v_mfma_f32_16x16x32_bf16 v[82:85], v[134:137], v[182:185], v[82:85]
	v_mfma_f32_16x16x32_bf16 v[74:77], v[142:145], v[182:185], v[74:77]
	v_mfma_f32_16x16x32_bf16 v[70:73], v[134:137], v[178:181], v[70:73]
	v_mfma_f32_16x16x32_bf16 v[66:69], v[142:145], v[178:181], v[66:69]
	s_add_u32 s52, s36, s48
	s_addc_u32 s53, s37, s49
	s_add_u32 s56, s52, 0x440000
	s_addc_u32 s57, s53, 0
	s_cmp_eq_u32 s48, 0x3fc0000
	s_cselect_b64 s[58:59], -1, 0
	s_and_b64 s[52:53], s[58:59], exec
	s_cselect_b32 s53, s31, s63
	s_cselect_b32 s52, s61, s62
	s_cselect_b32 s57, s19, s57
	s_cselect_b32 s56, s29, s56
	s_barrier
	s_andn2_b64 s[42:43], exec, s[40:41]
	s_andn2_b64 vcc, exec, s[40:41]
	s_cbranch_vccnz .LBB0_1291
	ds_read_b128 v[174:177], v231 offset:16384
	ds_read_b128 v[190:193], v231 offset:17408
	ds_read_b128 v[170:173], v231 offset:18432
	ds_read_b128 v[186:189], v231 offset:19456
	ds_read_b128 v[166:169], v231 offset:20480
	ds_read_b128 v[182:185], v231 offset:21504
	ds_read_b128 v[162:165], v231 offset:22528
	ds_read_b128 v[178:181], v231 offset:23552
.LBB0_1291:
	s_mov_b32 m0, s9
	s_add_u32 s68, s52, 0x4000
	global_load_lds_dwordx4 v194, s[52:53]
	s_mov_b32 m0, s10
	s_addc_u32 s69, s53, 0
	global_load_lds_dwordx4 v196, s[52:53]
	s_mov_b32 m0, s11
	s_and_b64 vcc, exec, s[42:43]
	global_load_lds_dwordx4 v194, s[68:69]
	s_mov_b32 m0, s12
	s_nop 0
	global_load_lds_dwordx4 v196, s[68:69]
	s_mov_b64 s[98:99], s[56:57]
	s_waitcnt vmcnt(6) lgkmcnt(0)
	s_barrier
	s_cbranch_vccnz .LBB0_1293
	s_waitcnt lgkmcnt(0)
	v_mfma_f32_16x16x32_bf16 v[62:65], v[146:149], v[174:177], v[62:65]
	v_mfma_f32_16x16x32_bf16 v[58:61], v[154:157], v[174:177], v[58:61]
	v_mfma_f32_16x16x32_bf16 v[46:49], v[146:149], v[170:173], v[46:49]
	v_mfma_f32_16x16x32_bf16 v[42:45], v[154:157], v[170:173], v[42:45]
	v_mfma_f32_16x16x32_bf16 v[30:33], v[146:149], v[166:169], v[30:33]
	v_mfma_f32_16x16x32_bf16 v[26:29], v[154:157], v[166:169], v[26:29]
	v_mfma_f32_16x16x32_bf16 v[14:17], v[146:149], v[162:165], v[14:17]
	v_mfma_f32_16x16x32_bf16 v[10:13], v[154:157], v[162:165], v[10:13]
	v_mfma_f32_16x16x32_bf16 v[62:65], v[150:153], v[190:193], v[62:65]
	v_mfma_f32_16x16x32_bf16 v[58:61], v[158:161], v[190:193], v[58:61]
	v_mfma_f32_16x16x32_bf16 v[46:49], v[150:153], v[186:189], v[46:49]
	v_mfma_f32_16x16x32_bf16 v[42:45], v[158:161], v[186:189], v[42:45]
	v_mfma_f32_16x16x32_bf16 v[30:33], v[150:153], v[182:185], v[30:33]
	v_mfma_f32_16x16x32_bf16 v[26:29], v[158:161], v[182:185], v[26:29]
	v_mfma_f32_16x16x32_bf16 v[14:17], v[150:153], v[178:181], v[14:17]
	v_mfma_f32_16x16x32_bf16 v[10:13], v[158:161], v[178:181], v[10:13]
	v_mfma_f32_16x16x32_bf16 v[54:57], v[130:133], v[174:177], v[54:57]
	v_mfma_f32_16x16x32_bf16 v[50:53], v[138:141], v[174:177], v[50:53]
	v_mfma_f32_16x16x32_bf16 v[38:41], v[130:133], v[170:173], v[38:41]
	v_mfma_f32_16x16x32_bf16 v[34:37], v[138:141], v[170:173], v[34:37]
	v_mfma_f32_16x16x32_bf16 v[22:25], v[130:133], v[166:169], v[22:25]
	v_mfma_f32_16x16x32_bf16 v[18:21], v[138:141], v[166:169], v[18:21]
	v_mfma_f32_16x16x32_bf16 v[6:9], v[130:133], v[162:165], v[6:9]
	v_mfma_f32_16x16x32_bf16 v[2:5], v[138:141], v[162:165], v[2:5]
	v_mfma_f32_16x16x32_bf16 v[54:57], v[134:137], v[190:193], v[54:57]
	v_mfma_f32_16x16x32_bf16 v[50:53], v[142:145], v[190:193], v[50:53]
	v_mfma_f32_16x16x32_bf16 v[38:41], v[134:137], v[186:189], v[38:41]
	v_mfma_f32_16x16x32_bf16 v[34:37], v[142:145], v[186:189], v[34:37]
	v_mfma_f32_16x16x32_bf16 v[22:25], v[134:137], v[182:185], v[22:25]
	v_mfma_f32_16x16x32_bf16 v[18:21], v[142:145], v[182:185], v[18:21]
	v_mfma_f32_16x16x32_bf16 v[6:9], v[134:137], v[178:181], v[6:9]
	v_mfma_f32_16x16x32_bf16 v[2:5], v[142:145], v[178:181], v[2:5]
.LBB0_1293:
	s_and_b64 vcc, s[34:35], s[58:59]
	v_cndmask_b32_e64 v131, v221, 0, vcc
	v_cndmask_b32_e32 v130, v220, v198, vcc
	v_lshl_add_u64 v[234:235], s[56:57], 0, v[130:131]
	s_barrier
	s_mov_b32 m0, s8
	s_nop 0
	global_load_lds_dwordx4 v194, s[98:99]
	s_mov_b32 m0, s13
	s_nop 0
	global_load_lds_dwordx4 v196, s[98:99]
	v_add_u32_e32 v130, 0x18000, v229
	v_add_u32_e32 v142, 0x1c000, v229
	ds_read_b128 v[146:149], v130
	ds_read_b128 v[150:153], v130 offset:1024
	ds_read_b128 v[154:157], v130 offset:2048
	ds_read_b128 v[158:161], v130 offset:3072
	ds_read_b128 v[130:133], v142
	ds_read_b128 v[134:137], v142 offset:1024
	ds_read_b128 v[138:141], v142 offset:2048
	ds_read_b128 v[142:145], v142 offset:3072
	s_mov_b32 m0, s14
	v_lshl_add_u64 v[236:237], v[234:235], 0, v[194:195]
	s_waitcnt lgkmcnt(0)
	ds_read_b128 v[174:177], v231 offset:32768
	ds_read_b128 v[190:193], v231 offset:33792
	ds_read_b128 v[170:173], v231 offset:34816
	ds_read_b128 v[186:189], v231 offset:35840
	ds_read_b128 v[166:169], v231 offset:36864
	ds_read_b128 v[182:185], v231 offset:37888
	ds_read_b128 v[162:165], v231 offset:38912
	ds_read_b128 v[178:181], v231 offset:39936
	global_load_lds_dwordx4 v[236:237], off
	v_lshl_add_u64 v[234:235], v[234:235], 0, v[196:197]
	s_mov_b32 m0, s15
	s_nop 0
	global_load_lds_dwordx4 v[234:235], off
	s_waitcnt vmcnt(8) lgkmcnt(0)
	s_barrier
	v_mfma_f32_16x16x32_bf16 v[126:129], v[146:149], v[174:177], v[126:129]
	v_mfma_f32_16x16x32_bf16 v[122:125], v[154:157], v[174:177], v[122:125]
	v_mfma_f32_16x16x32_bf16 v[118:121], v[146:149], v[170:173], v[118:121]
	v_mfma_f32_16x16x32_bf16 v[110:113], v[154:157], v[170:173], v[110:113]
	v_mfma_f32_16x16x32_bf16 v[102:105], v[146:149], v[166:169], v[102:105]
	v_mfma_f32_16x16x32_bf16 v[94:97], v[154:157], v[166:169], v[94:97]
	v_mfma_f32_16x16x32_bf16 v[86:89], v[146:149], v[162:165], v[86:89]
	v_mfma_f32_16x16x32_bf16 v[78:81], v[154:157], v[162:165], v[78:81]
	v_mfma_f32_16x16x32_bf16 v[126:129], v[150:153], v[190:193], v[126:129]
	v_mfma_f32_16x16x32_bf16 v[122:125], v[158:161], v[190:193], v[122:125]
	v_mfma_f32_16x16x32_bf16 v[118:121], v[150:153], v[186:189], v[118:121]
	v_mfma_f32_16x16x32_bf16 v[110:113], v[158:161], v[186:189], v[110:113]
	v_mfma_f32_16x16x32_bf16 v[102:105], v[150:153], v[182:185], v[102:105]
	v_mfma_f32_16x16x32_bf16 v[94:97], v[158:161], v[182:185], v[94:97]
	v_mfma_f32_16x16x32_bf16 v[86:89], v[150:153], v[178:181], v[86:89]
	v_mfma_f32_16x16x32_bf16 v[78:81], v[158:161], v[178:181], v[78:81]
	v_mfma_f32_16x16x32_bf16 v[114:117], v[130:133], v[174:177], v[114:117]
	v_mfma_f32_16x16x32_bf16 v[106:109], v[138:141], v[174:177], v[106:109]
	v_mfma_f32_16x16x32_bf16 v[98:101], v[130:133], v[170:173], v[98:101]
	v_mfma_f32_16x16x32_bf16 v[90:93], v[138:141], v[170:173], v[90:93]
	v_mfma_f32_16x16x32_bf16 v[82:85], v[130:133], v[166:169], v[82:85]
	v_mfma_f32_16x16x32_bf16 v[74:77], v[138:141], v[166:169], v[74:77]
	v_mfma_f32_16x16x32_bf16 v[70:73], v[130:133], v[162:165], v[70:73]
	v_mfma_f32_16x16x32_bf16 v[66:69], v[138:141], v[162:165], v[66:69]
	v_mfma_f32_16x16x32_bf16 v[114:117], v[134:137], v[190:193], v[114:117]
	v_mfma_f32_16x16x32_bf16 v[106:109], v[142:145], v[190:193], v[106:109]
	v_mfma_f32_16x16x32_bf16 v[98:101], v[134:137], v[186:189], v[98:101]
	v_mfma_f32_16x16x32_bf16 v[90:93], v[142:145], v[186:189], v[90:93]
	v_mfma_f32_16x16x32_bf16 v[82:85], v[134:137], v[182:185], v[82:85]
	v_mfma_f32_16x16x32_bf16 v[74:77], v[142:145], v[182:185], v[74:77]
	v_mfma_f32_16x16x32_bf16 v[70:73], v[134:137], v[178:181], v[70:73]
	v_mfma_f32_16x16x32_bf16 v[66:69], v[142:145], v[178:181], v[66:69]
	s_add_u32 s58, s52, 0x40000
	s_addc_u32 s59, s53, 0
	s_add_u32 s56, s56, 0x220000
	s_addc_u32 s57, s57, 0
	s_barrier
	s_and_b64 vcc, exec, s[42:43]
	s_cbranch_vccnz .LBB0_1295
	ds_read_b128 v[174:177], v231 offset:49152
	ds_read_b128 v[190:193], v231 offset:50176
	ds_read_b128 v[170:173], v231 offset:51200
	ds_read_b128 v[186:189], v231 offset:52224
	ds_read_b128 v[166:169], v231 offset:53248
	ds_read_b128 v[182:185], v231 offset:54272
	ds_read_b128 v[162:165], v231 offset:55296
	ds_read_b128 v[178:181], v231 offset:56320
.LBB0_1295:
	s_mov_b32 m0, s16
	s_add_u32 s52, s52, 0x44000
	global_load_lds_dwordx4 v194, s[58:59]
	s_mov_b32 m0, s17
	s_addc_u32 s53, s53, 0
	global_load_lds_dwordx4 v196, s[58:59]
	s_mov_b32 m0, s55
	s_and_b64 vcc, exec, s[42:43]
	global_load_lds_dwordx4 v194, s[52:53]
	s_mov_b32 m0, s60
	s_nop 0
	global_load_lds_dwordx4 v196, s[52:53]
	s_mov_b64 s[100:101], s[56:57]
	s_waitcnt vmcnt(6) lgkmcnt(0)
	s_barrier
	s_cbranch_vccnz .LBB0_1288
	s_waitcnt lgkmcnt(0)
	v_mfma_f32_16x16x32_bf16 v[62:65], v[146:149], v[174:177], v[62:65]
	v_mfma_f32_16x16x32_bf16 v[58:61], v[154:157], v[174:177], v[58:61]
	v_mfma_f32_16x16x32_bf16 v[46:49], v[146:149], v[170:173], v[46:49]
	v_mfma_f32_16x16x32_bf16 v[42:45], v[154:157], v[170:173], v[42:45]
	v_mfma_f32_16x16x32_bf16 v[30:33], v[146:149], v[166:169], v[30:33]
	v_mfma_f32_16x16x32_bf16 v[26:29], v[154:157], v[166:169], v[26:29]
	v_mfma_f32_16x16x32_bf16 v[14:17], v[146:149], v[162:165], v[14:17]
	v_mfma_f32_16x16x32_bf16 v[10:13], v[154:157], v[162:165], v[10:13]
	v_mfma_f32_16x16x32_bf16 v[62:65], v[150:153], v[190:193], v[62:65]
	v_mfma_f32_16x16x32_bf16 v[58:61], v[158:161], v[190:193], v[58:61]
	v_mfma_f32_16x16x32_bf16 v[46:49], v[150:153], v[186:189], v[46:49]
	v_mfma_f32_16x16x32_bf16 v[42:45], v[158:161], v[186:189], v[42:45]
	v_mfma_f32_16x16x32_bf16 v[30:33], v[150:153], v[182:185], v[30:33]
	v_mfma_f32_16x16x32_bf16 v[26:29], v[158:161], v[182:185], v[26:29]
	v_mfma_f32_16x16x32_bf16 v[14:17], v[150:153], v[178:181], v[14:17]
	v_mfma_f32_16x16x32_bf16 v[10:13], v[158:161], v[178:181], v[10:13]
	v_mfma_f32_16x16x32_bf16 v[54:57], v[130:133], v[174:177], v[54:57]
	v_mfma_f32_16x16x32_bf16 v[50:53], v[138:141], v[174:177], v[50:53]
	v_mfma_f32_16x16x32_bf16 v[38:41], v[130:133], v[170:173], v[38:41]
	v_mfma_f32_16x16x32_bf16 v[34:37], v[138:141], v[170:173], v[34:37]
	v_mfma_f32_16x16x32_bf16 v[22:25], v[130:133], v[166:169], v[22:25]
	v_mfma_f32_16x16x32_bf16 v[18:21], v[138:141], v[166:169], v[18:21]
	v_mfma_f32_16x16x32_bf16 v[6:9], v[130:133], v[162:165], v[6:9]
	v_mfma_f32_16x16x32_bf16 v[2:5], v[138:141], v[162:165], v[2:5]
	v_mfma_f32_16x16x32_bf16 v[54:57], v[134:137], v[190:193], v[54:57]
	v_mfma_f32_16x16x32_bf16 v[50:53], v[142:145], v[190:193], v[50:53]
	v_mfma_f32_16x16x32_bf16 v[38:41], v[134:137], v[186:189], v[38:41]
	v_mfma_f32_16x16x32_bf16 v[34:37], v[142:145], v[186:189], v[34:37]
	v_mfma_f32_16x16x32_bf16 v[22:25], v[134:137], v[182:185], v[22:25]
	v_mfma_f32_16x16x32_bf16 v[18:21], v[142:145], v[182:185], v[18:21]
	v_mfma_f32_16x16x32_bf16 v[6:9], v[134:137], v[178:181], v[6:9]
	v_mfma_f32_16x16x32_bf16 v[2:5], v[142:145], v[178:181], v[2:5]
	s_branch .LBB0_1288

.LBB0_1611:
	s_add_i32 s62, s62, 2
	s_add_u32 s60, s60, 0x80000
	s_addc_u32 s61, s61, 0
	s_add_u32 s48, s48, 0x440000
	s_addc_u32 s49, s49, 0
	s_cmp_gt_u32 s62, 29
	s_barrier
	s_cbranch_scc1 .LBB0_1620
.LBB0_1612:
	s_mov_b32 m0, s54
	s_nop 0
	global_load_lds_dwordx4 v194, s[100:101]
	s_mov_b32 m0, s55
	s_nop 0
	global_load_lds_dwordx4 v196, s[100:101]
	v_add_u32_e32 v1, 0x10000, v232
	ds_read_b128 v[146:149], v1
	ds_read_b128 v[150:153], v1 offset:1024
	ds_read_b128 v[154:157], v1 offset:2048
	ds_read_b128 v[158:161], v1 offset:3072
	v_add_u32_e32 v1, 0x14000, v232
	ds_read_b128 v[130:133], v1
	ds_read_b128 v[134:137], v1 offset:1024
	ds_read_b128 v[138:141], v1 offset:2048
	ds_read_b128 v[142:145], v1 offset:3072
	v_lshl_add_u64 v[236:237], v[226:227], 0, s[48:49]
	s_add_i32 m0, s9, 0xc000
	s_waitcnt lgkmcnt(0)
	ds_read_b128 v[174:177], v233
	ds_read_b128 v[190:193], v233 offset:1024
	ds_read_b128 v[170:173], v233 offset:2048
	ds_read_b128 v[186:189], v233 offset:3072
	ds_read_b128 v[166:169], v233 offset:4096
	ds_read_b128 v[182:185], v233 offset:5120
	ds_read_b128 v[162:165], v233 offset:6144
	ds_read_b128 v[178:181], v233 offset:7168
	global_load_lds_dwordx4 v[236:237], off
	v_lshl_add_u64 v[236:237], v[228:229], 0, s[48:49]
	s_add_i32 m0, s9, 0xe000
	s_nop 0
	global_load_lds_dwordx4 v[236:237], off
	s_waitcnt vmcnt(8) lgkmcnt(0)
	s_barrier
	v_mfma_f32_16x16x32_bf16 v[126:129], v[146:149], v[174:177], v[126:129]
	v_mfma_f32_16x16x32_bf16 v[122:125], v[154:157], v[174:177], v[122:125]
	v_mfma_f32_16x16x32_bf16 v[118:121], v[146:149], v[170:173], v[118:121]
	v_mfma_f32_16x16x32_bf16 v[110:113], v[154:157], v[170:173], v[110:113]
	v_mfma_f32_16x16x32_bf16 v[102:105], v[146:149], v[166:169], v[102:105]
	v_mfma_f32_16x16x32_bf16 v[94:97], v[154:157], v[166:169], v[94:97]
	v_mfma_f32_16x16x32_bf16 v[86:89], v[146:149], v[162:165], v[86:89]
	v_mfma_f32_16x16x32_bf16 v[78:81], v[154:157], v[162:165], v[78:81]
	v_mfma_f32_16x16x32_bf16 v[126:129], v[150:153], v[190:193], v[126:129]
	v_mfma_f32_16x16x32_bf16 v[122:125], v[158:161], v[190:193], v[122:125]
	v_mfma_f32_16x16x32_bf16 v[118:121], v[150:153], v[186:189], v[118:121]
	v_mfma_f32_16x16x32_bf16 v[110:113], v[158:161], v[186:189], v[110:113]
	v_mfma_f32_16x16x32_bf16 v[102:105], v[150:153], v[182:185], v[102:105]
	v_mfma_f32_16x16x32_bf16 v[94:97], v[158:161], v[182:185], v[94:97]
	v_mfma_f32_16x16x32_bf16 v[86:89], v[150:153], v[178:181], v[86:89]
	v_mfma_f32_16x16x32_bf16 v[78:81], v[158:161], v[178:181], v[78:81]
	v_mfma_f32_16x16x32_bf16 v[114:117], v[130:133], v[174:177], v[114:117]
	v_mfma_f32_16x16x32_bf16 v[106:109], v[138:141], v[174:177], v[106:109]
	v_mfma_f32_16x16x32_bf16 v[98:101], v[130:133], v[170:173], v[98:101]
	v_mfma_f32_16x16x32_bf16 v[90:93], v[138:141], v[170:173], v[90:93]
	v_mfma_f32_16x16x32_bf16 v[82:85], v[130:133], v[166:169], v[82:85]
	v_mfma_f32_16x16x32_bf16 v[74:77], v[138:141], v[166:169], v[74:77]
	v_mfma_f32_16x16x32_bf16 v[70:73], v[130:133], v[162:165], v[70:73]
	v_mfma_f32_16x16x32_bf16 v[66:69], v[138:141], v[162:165], v[66:69]
	v_mfma_f32_16x16x32_bf16 v[114:117], v[134:137], v[190:193], v[114:117]
	v_mfma_f32_16x16x32_bf16 v[106:109], v[142:145], v[190:193], v[106:109]
	v_mfma_f32_16x16x32_bf16 v[98:101], v[134:137], v[186:189], v[98:101]
	v_mfma_f32_16x16x32_bf16 v[90:93], v[142:145], v[186:189], v[90:93]
	v_mfma_f32_16x16x32_bf16 v[82:85], v[134:137], v[182:185], v[82:85]
	v_mfma_f32_16x16x32_bf16 v[74:77], v[142:145], v[182:185], v[74:77]
	v_mfma_f32_16x16x32_bf16 v[70:73], v[134:137], v[178:181], v[70:73]
	v_mfma_f32_16x16x32_bf16 v[66:69], v[142:145], v[178:181], v[66:69]
	s_add_u32 s50, s46, s48
	s_addc_u32 s51, s47, s49
	s_add_u32 s52, s50, 0x440000
	s_addc_u32 s53, s51, 0
	s_cmp_eq_u32 s48, 0x3fc0000
	s_cselect_b64 s[56:57], -1, 0
	s_and_b64 s[50:51], s[56:57], exec
	s_cselect_b32 s51, s31, s61
	s_cselect_b32 s50, s35, s60
	s_cselect_b32 s53, s19, s53
	s_cselect_b32 s52, s20, s52
	s_barrier
	s_andn2_b64 s[42:43], exec, s[40:41]
	s_andn2_b64 vcc, exec, s[40:41]
	s_cbranch_vccnz .LBB0_1614
	ds_read_b128 v[174:177], v233 offset:16384
	ds_read_b128 v[190:193], v233 offset:17408
	ds_read_b128 v[170:173], v233 offset:18432
	ds_read_b128 v[186:189], v233 offset:19456
	ds_read_b128 v[166:169], v233 offset:20480
	ds_read_b128 v[182:185], v233 offset:21504
	ds_read_b128 v[162:165], v233 offset:22528
	ds_read_b128 v[178:181], v233 offset:23552
.LBB0_1614:
	s_mov_b32 m0, s10
	s_add_u32 s68, s50, 0x4000
	global_load_lds_dwordx4 v194, s[50:51]
	s_mov_b32 m0, s11
	s_addc_u32 s69, s51, 0
	global_load_lds_dwordx4 v196, s[50:51]
	s_mov_b32 m0, s12
	s_and_b64 vcc, exec, s[42:43]
	global_load_lds_dwordx4 v194, s[68:69]
	s_mov_b32 m0, s13
	s_nop 0
	global_load_lds_dwordx4 v196, s[68:69]
	s_mov_b64 s[98:99], s[52:53]
	s_waitcnt vmcnt(6) lgkmcnt(0)
	s_barrier
	s_cbranch_vccnz .LBB0_1616
	s_waitcnt lgkmcnt(0)
	v_mfma_f32_16x16x32_bf16 v[62:65], v[146:149], v[174:177], v[62:65]
	v_mfma_f32_16x16x32_bf16 v[58:61], v[154:157], v[174:177], v[58:61]
	v_mfma_f32_16x16x32_bf16 v[46:49], v[146:149], v[170:173], v[46:49]
	v_mfma_f32_16x16x32_bf16 v[42:45], v[154:157], v[170:173], v[42:45]
	v_mfma_f32_16x16x32_bf16 v[30:33], v[146:149], v[166:169], v[30:33]
	v_mfma_f32_16x16x32_bf16 v[26:29], v[154:157], v[166:169], v[26:29]
	v_mfma_f32_16x16x32_bf16 v[14:17], v[146:149], v[162:165], v[14:17]
	v_mfma_f32_16x16x32_bf16 v[10:13], v[154:157], v[162:165], v[10:13]
	v_mfma_f32_16x16x32_bf16 v[62:65], v[150:153], v[190:193], v[62:65]
	v_mfma_f32_16x16x32_bf16 v[58:61], v[158:161], v[190:193], v[58:61]
	v_mfma_f32_16x16x32_bf16 v[46:49], v[150:153], v[186:189], v[46:49]
	v_mfma_f32_16x16x32_bf16 v[42:45], v[158:161], v[186:189], v[42:45]
	v_mfma_f32_16x16x32_bf16 v[30:33], v[150:153], v[182:185], v[30:33]
	v_mfma_f32_16x16x32_bf16 v[26:29], v[158:161], v[182:185], v[26:29]
	v_mfma_f32_16x16x32_bf16 v[14:17], v[150:153], v[178:181], v[14:17]
	v_mfma_f32_16x16x32_bf16 v[10:13], v[158:161], v[178:181], v[10:13]
	v_mfma_f32_16x16x32_bf16 v[54:57], v[130:133], v[174:177], v[54:57]
	v_mfma_f32_16x16x32_bf16 v[50:53], v[138:141], v[174:177], v[50:53]
	v_mfma_f32_16x16x32_bf16 v[38:41], v[130:133], v[170:173], v[38:41]
	v_mfma_f32_16x16x32_bf16 v[34:37], v[138:141], v[170:173], v[34:37]
	v_mfma_f32_16x16x32_bf16 v[22:25], v[130:133], v[166:169], v[22:25]
	v_mfma_f32_16x16x32_bf16 v[18:21], v[138:141], v[166:169], v[18:21]
	v_mfma_f32_16x16x32_bf16 v[6:9], v[130:133], v[162:165], v[6:9]
	v_mfma_f32_16x16x32_bf16 v[2:5], v[138:141], v[162:165], v[2:5]
	v_mfma_f32_16x16x32_bf16 v[54:57], v[134:137], v[190:193], v[54:57]
	v_mfma_f32_16x16x32_bf16 v[50:53], v[142:145], v[190:193], v[50:53]
	v_mfma_f32_16x16x32_bf16 v[38:41], v[134:137], v[186:189], v[38:41]
	v_mfma_f32_16x16x32_bf16 v[34:37], v[142:145], v[186:189], v[34:37]
	v_mfma_f32_16x16x32_bf16 v[22:25], v[134:137], v[182:185], v[22:25]
	v_mfma_f32_16x16x32_bf16 v[18:21], v[142:145], v[182:185], v[18:21]
	v_mfma_f32_16x16x32_bf16 v[6:9], v[134:137], v[178:181], v[6:9]
	v_mfma_f32_16x16x32_bf16 v[2:5], v[142:145], v[178:181], v[2:5]
.LBB0_1616:
	s_and_b64 vcc, s[38:39], s[56:57]
	v_cndmask_b32_e64 v131, v225, 0, vcc
	v_cndmask_b32_e32 v130, v224, v198, vcc
	v_lshl_add_u64 v[236:237], s[52:53], 0, v[130:131]
	s_barrier
	s_mov_b32 m0, s9
	s_nop 0
	global_load_lds_dwordx4 v194, s[98:99]
	s_mov_b32 m0, s14
	s_nop 0
	global_load_lds_dwordx4 v196, s[98:99]
	v_add_u32_e32 v1, 0x18000, v232
	ds_read_b128 v[146:149], v1
	ds_read_b128 v[150:153], v1 offset:1024
	ds_read_b128 v[154:157], v1 offset:2048
	ds_read_b128 v[158:161], v1 offset:3072
	v_add_u32_e32 v1, 0x1c000, v232
	ds_read_b128 v[130:133], v1
	ds_read_b128 v[134:137], v1 offset:1024
	ds_read_b128 v[138:141], v1 offset:2048
	ds_read_b128 v[142:145], v1 offset:3072
	s_mov_b32 m0, s15
	v_lshl_add_u64 v[238:239], v[236:237], 0, v[194:195]
	s_waitcnt lgkmcnt(0)
	ds_read_b128 v[174:177], v233 offset:32768
	ds_read_b128 v[190:193], v233 offset:33792
	ds_read_b128 v[170:173], v233 offset:34816
	ds_read_b128 v[186:189], v233 offset:35840
	ds_read_b128 v[166:169], v233 offset:36864
	ds_read_b128 v[182:185], v233 offset:37888
	ds_read_b128 v[162:165], v233 offset:38912
	ds_read_b128 v[178:181], v233 offset:39936
	global_load_lds_dwordx4 v[238:239], off
	v_lshl_add_u64 v[236:237], v[236:237], 0, v[196:197]
	s_mov_b32 m0, s16
	s_nop 0
	global_load_lds_dwordx4 v[236:237], off
	s_waitcnt vmcnt(8) lgkmcnt(0)
	s_barrier
	v_mfma_f32_16x16x32_bf16 v[126:129], v[146:149], v[174:177], v[126:129]
	v_mfma_f32_16x16x32_bf16 v[122:125], v[154:157], v[174:177], v[122:125]
	v_mfma_f32_16x16x32_bf16 v[118:121], v[146:149], v[170:173], v[118:121]
	v_mfma_f32_16x16x32_bf16 v[110:113], v[154:157], v[170:173], v[110:113]
	v_mfma_f32_16x16x32_bf16 v[102:105], v[146:149], v[166:169], v[102:105]
	v_mfma_f32_16x16x32_bf16 v[94:97], v[154:157], v[166:169], v[94:97]
	v_mfma_f32_16x16x32_bf16 v[86:89], v[146:149], v[162:165], v[86:89]
	v_mfma_f32_16x16x32_bf16 v[78:81], v[154:157], v[162:165], v[78:81]
	v_mfma_f32_16x16x32_bf16 v[126:129], v[150:153], v[190:193], v[126:129]
	v_mfma_f32_16x16x32_bf16 v[122:125], v[158:161], v[190:193], v[122:125]
	v_mfma_f32_16x16x32_bf16 v[118:121], v[150:153], v[186:189], v[118:121]
	v_mfma_f32_16x16x32_bf16 v[110:113], v[158:161], v[186:189], v[110:113]
	v_mfma_f32_16x16x32_bf16 v[102:105], v[150:153], v[182:185], v[102:105]
	v_mfma_f32_16x16x32_bf16 v[94:97], v[158:161], v[182:185], v[94:97]
	v_mfma_f32_16x16x32_bf16 v[86:89], v[150:153], v[178:181], v[86:89]
	v_mfma_f32_16x16x32_bf16 v[78:81], v[158:161], v[178:181], v[78:81]
	v_mfma_f32_16x16x32_bf16 v[114:117], v[130:133], v[174:177], v[114:117]
	v_mfma_f32_16x16x32_bf16 v[106:109], v[138:141], v[174:177], v[106:109]
	v_mfma_f32_16x16x32_bf16 v[98:101], v[130:133], v[170:173], v[98:101]
	v_mfma_f32_16x16x32_bf16 v[90:93], v[138:141], v[170:173], v[90:93]
	v_mfma_f32_16x16x32_bf16 v[82:85], v[130:133], v[166:169], v[82:85]
	v_mfma_f32_16x16x32_bf16 v[74:77], v[138:141], v[166:169], v[74:77]
	v_mfma_f32_16x16x32_bf16 v[70:73], v[130:133], v[162:165], v[70:73]
	v_mfma_f32_16x16x32_bf16 v[66:69], v[138:141], v[162:165], v[66:69]
	v_mfma_f32_16x16x32_bf16 v[114:117], v[134:137], v[190:193], v[114:117]
	v_mfma_f32_16x16x32_bf16 v[106:109], v[142:145], v[190:193], v[106:109]
	v_mfma_f32_16x16x32_bf16 v[98:101], v[134:137], v[186:189], v[98:101]
	v_mfma_f32_16x16x32_bf16 v[90:93], v[142:145], v[186:189], v[90:93]
	v_mfma_f32_16x16x32_bf16 v[82:85], v[134:137], v[182:185], v[82:85]
	v_mfma_f32_16x16x32_bf16 v[74:77], v[142:145], v[182:185], v[74:77]
	v_mfma_f32_16x16x32_bf16 v[70:73], v[134:137], v[178:181], v[70:73]
	v_mfma_f32_16x16x32_bf16 v[66:69], v[142:145], v[178:181], v[66:69]
	s_add_u32 s56, s50, 0x40000
	s_addc_u32 s57, s51, 0
	s_add_u32 s52, s52, 0x220000
	s_addc_u32 s53, s53, 0
	s_barrier
	s_and_b64 vcc, exec, s[42:43]
	s_cbranch_vccnz .LBB0_1618
	ds_read_b128 v[174:177], v233 offset:49152
	ds_read_b128 v[190:193], v233 offset:50176
	ds_read_b128 v[170:173], v233 offset:51200
	ds_read_b128 v[186:189], v233 offset:52224
	ds_read_b128 v[166:169], v233 offset:53248
	ds_read_b128 v[182:185], v233 offset:54272
	ds_read_b128 v[162:165], v233 offset:55296
	ds_read_b128 v[178:181], v233 offset:56320
.LBB0_1618:
	s_mov_b32 m0, s17
	s_add_u32 s50, s50, 0x44000
	global_load_lds_dwordx4 v194, s[56:57]
	s_mov_b32 m0, s29
	s_addc_u32 s51, s51, 0
	global_load_lds_dwordx4 v196, s[56:57]
	s_mov_b32 m0, s58
	s_and_b64 vcc, exec, s[42:43]
	global_load_lds_dwordx4 v194, s[50:51]
	s_mov_b32 m0, s59
	s_nop 0
	global_load_lds_dwordx4 v196, s[50:51]
	s_mov_b64 s[100:101], s[52:53]
	s_waitcnt vmcnt(6) lgkmcnt(0)
	s_barrier
	s_cbranch_vccnz .LBB0_1611
	s_waitcnt lgkmcnt(0)
	v_mfma_f32_16x16x32_bf16 v[62:65], v[146:149], v[174:177], v[62:65]
	v_mfma_f32_16x16x32_bf16 v[58:61], v[154:157], v[174:177], v[58:61]
	v_mfma_f32_16x16x32_bf16 v[46:49], v[146:149], v[170:173], v[46:49]
	v_mfma_f32_16x16x32_bf16 v[42:45], v[154:157], v[170:173], v[42:45]
	v_mfma_f32_16x16x32_bf16 v[30:33], v[146:149], v[166:169], v[30:33]
	v_mfma_f32_16x16x32_bf16 v[26:29], v[154:157], v[166:169], v[26:29]
	v_mfma_f32_16x16x32_bf16 v[14:17], v[146:149], v[162:165], v[14:17]
	v_mfma_f32_16x16x32_bf16 v[10:13], v[154:157], v[162:165], v[10:13]
	v_mfma_f32_16x16x32_bf16 v[62:65], v[150:153], v[190:193], v[62:65]
	v_mfma_f32_16x16x32_bf16 v[58:61], v[158:161], v[190:193], v[58:61]
	v_mfma_f32_16x16x32_bf16 v[46:49], v[150:153], v[186:189], v[46:49]
	v_mfma_f32_16x16x32_bf16 v[42:45], v[158:161], v[186:189], v[42:45]
	v_mfma_f32_16x16x32_bf16 v[30:33], v[150:153], v[182:185], v[30:33]
	v_mfma_f32_16x16x32_bf16 v[26:29], v[158:161], v[182:185], v[26:29]
	v_mfma_f32_16x16x32_bf16 v[14:17], v[150:153], v[178:181], v[14:17]
	v_mfma_f32_16x16x32_bf16 v[10:13], v[158:161], v[178:181], v[10:13]
	v_mfma_f32_16x16x32_bf16 v[54:57], v[130:133], v[174:177], v[54:57]
	v_mfma_f32_16x16x32_bf16 v[50:53], v[138:141], v[174:177], v[50:53]
	v_mfma_f32_16x16x32_bf16 v[38:41], v[130:133], v[170:173], v[38:41]
	v_mfma_f32_16x16x32_bf16 v[34:37], v[138:141], v[170:173], v[34:37]
	v_mfma_f32_16x16x32_bf16 v[22:25], v[130:133], v[166:169], v[22:25]
	v_mfma_f32_16x16x32_bf16 v[18:21], v[138:141], v[166:169], v[18:21]
	v_mfma_f32_16x16x32_bf16 v[6:9], v[130:133], v[162:165], v[6:9]
	v_mfma_f32_16x16x32_bf16 v[2:5], v[138:141], v[162:165], v[2:5]
	v_mfma_f32_16x16x32_bf16 v[54:57], v[134:137], v[190:193], v[54:57]
	v_mfma_f32_16x16x32_bf16 v[50:53], v[142:145], v[190:193], v[50:53]
	v_mfma_f32_16x16x32_bf16 v[38:41], v[134:137], v[186:189], v[38:41]
	v_mfma_f32_16x16x32_bf16 v[34:37], v[142:145], v[186:189], v[34:37]
	v_mfma_f32_16x16x32_bf16 v[22:25], v[134:137], v[182:185], v[22:25]
	v_mfma_f32_16x16x32_bf16 v[18:21], v[142:145], v[182:185], v[18:21]
	v_mfma_f32_16x16x32_bf16 v[6:9], v[134:137], v[178:181], v[6:9]
	v_mfma_f32_16x16x32_bf16 v[2:5], v[142:145], v[178:181], v[2:5]
	s_branch .LBB0_1611
